# speedup vs baseline: 1.1233x; 1.0193x over previous
; #define TILE_RC(t_, brow_, bcol_) do { const int wg_ = ((t_) & 7) * (nwg >> 3) + ((t_) >> 3); const int gid_ = wg_ / nig, fm_ = gid_ * 8, gsz_ = min(nM - fm_, 8); \
;     brow_ = (fm_ + ((wg_ % nig) % gsz_)) << 8; bcol_ = ((wg_ % nig) / gsz_) << 8; } while (0)
; #define LDA_(ks_, m_) (*(const bf16x8*)(SA(cur) + lds_byte2(wr * 128 + (m_) * 16 + fr, (ks_) * 32 + fq * 8)))
; #define LDB_(ks_, n_) (*(const bf16x8*)(SB(cur) + lds_byte2(wc * 64 + (n_) * 16 + fr, (ks_) * 32 + fq * 8)))
; __device__ __forceinline__ void gemm_run(const GemmDesc& g, char* shm) {
;     ...
;       if (kt + 1 < nt) { GLDS_STAGE(cur ^ 1, kt + 1); }
;       else if (t + (int)gridDim.x < nwg) {
;         int br, bc; TILE_RC(t + (int)gridDim.x, br, bc); SET_PTRS(br, bc); GLDS_STAGE(cur ^ 1, 0);
;       }
;       {
;     ...
;         bf16x8 Bf[2][4], Ar[3];
; #pragma unroll
;         for (int n = 0; n < 4; ++n) Bf[0][n] = LDB_(0, n);
;         Ar[0] = LDA_(0, 0); Ar[1] = LDA_(0, 1);
;         __builtin_amdgcn_sched_barrier(0);
; #pragma unroll
;         for (int st = 0; st < 16; ++st) {
;           const int ks = st >> 3, m = st & 7;
;           if (st + 2 < 16) Ar[(st + 2) % 3] = LDA_((st + 2) >> 3, (st + 2) & 7);
.LBB0_284:
	s_lshl_b32 s6, s60, 16
	v_mov_b32_e32 v152, s6
	v_add3_u32 v153, v152, v171, v170
	v_add3_u32 v232, v152, v171, v173
	ds_read_b128 v[128:131], v153 offset:32768
	ds_read_b128 v[144:147], v153 offset:34816
	ds_read_b128 v[148:151], v153 offset:36864
	ds_read_b128 v[154:157], v153 offset:38912
	ds_read_b128 v[204:207], v232 offset:0
	ds_read_b128 v[208:211], v232 offset:2048
	ds_read_b128 v[212:215], v232 offset:4096
	s_branch .Lg_comp
.Lg_norm:
	s_lshl_b32 s6, s60, 16
	v_mov_b32_e32 v152, s6
	v_add3_u32 v153, v152, v171, v170
	v_add3_u32 v232, v152, v171, v173
	ds_read_b128 v[128:131], v153 offset:32768
	ds_read_b128 v[144:147], v153 offset:34816
	ds_read_b128 v[148:151], v153 offset:36864
	ds_read_b128 v[154:157], v153 offset:38912
	ds_read_b128 v[204:207], v232 offset:0
	ds_read_b128 v[208:211], v232 offset:2048
	ds_read_b128 v[212:215], v232 offset:4096
	s_xor_b32 s4, s6, 0x10000
	v_readfirstlane_b32 s5, v137
	s_cmp_lt_u32 s38, s16
	s_cselect_b64 vcc, -1, 0
	s_add_i32 s4, s4, s5
	s_add_i32 s5, s39, s64
	s_add_i32 s7, s39, 0x80
	v_add_u32_e32 v239, s7, v192
	v_add_u32_e32 v240, s5, v193
	s_add_i32 m0, s4, 0x0
	v_cndmask_b32_e32 v239, v240, v239, vcc
	v_add_u32_e32 v241, s7, v202
	global_load_lds_dwordx4 v239, s[30:31]
	s_add_i32 m0, s4, 0x8000
	s_nop 0
	global_load_lds_dwordx4 v241, s[30:31]
	v_add_u32_e32 v239, s7, v194
	v_add_u32_e32 v240, s5, v196
	s_add_i32 m0, s4, 0x2000
	v_cndmask_b32_e32 v239, v240, v239, vcc
	v_add_u32_e32 v241, s7, v201
	global_load_lds_dwordx4 v239, s[30:31]
	s_add_i32 m0, s4, 0xa000
	s_nop 0
	global_load_lds_dwordx4 v241, s[30:31]
	v_add_u32_e32 v239, s7, v195
	v_add_u32_e32 v240, s5, v198
	s_add_i32 m0, s4, 0x4000
	v_cndmask_b32_e32 v239, v240, v239, vcc
	v_add_u32_e32 v241, s7, v200
	global_load_lds_dwordx4 v239, s[30:31]
	s_add_i32 m0, s4, 0xc000
	s_nop 0
	global_load_lds_dwordx4 v241, s[30:31]
	v_add_u32_e32 v239, s7, v197
	v_add_u32_e32 v240, s5, v199
	s_add_i32 m0, s4, 0x6000
	v_cndmask_b32_e32 v239, v240, v239, vcc
	v_add_u32_e32 v241, s7, v203
	global_load_lds_dwordx4 v239, s[30:31]
	s_add_i32 m0, s4, 0xe000
	s_nop 0
	global_load_lds_dwordx4 v241, s[30:31]
; #define LDA_(ks_, m_) (*(const bf16x8*)(SA(cur) + lds_byte2(wr * 128 + (m_) * 16 + fr, (ks_) * 32 + fq * 8)))
; #define LDB_(ks_, n_) (*(const bf16x8*)(SB(cur) + lds_byte2(wc * 64 + (n_) * 16 + fr, (ks_) * 32 + fq * 8)))
; __device__ __forceinline__ void gemm_run(const GemmDesc& g, char* shm) {
;     ...
;         __builtin_amdgcn_sched_barrier(0);
; #pragma unroll
;         for (int st = 0; st < 16; ++st) {
;           const int ks = st >> 3, m = st & 7;
;           if (st + 2 < 16) Ar[(st + 2) % 3] = LDA_((st + 2) >> 3, (st + 2) & 7);
;           if (st == 5) {
; #pragma unroll
;             for (int n = 0; n < 4; ++n) Bf[1][n] = LDB_(1, n);
;           }
; #pragma unroll
;           for (int n = 0; n < 4; ++n)
;             acc[m][n] = __builtin_amdgcn_mfma_f32_16x16x32_bf16(Bf[ks][n], Ar[st % 3], acc[m][n], 0, 0, 0);
;           __builtin_amdgcn_sched_barrier(0);
;         }
.Lg_comp:
	s_waitcnt lgkmcnt(2)
	v_mfma_f32_16x16x32_bf16 v[124:127], v[128:131], v[204:207], v[124:127]
	ds_read_b128 v[240:243], v232 offset:6144
	v_mfma_f32_16x16x32_bf16 v[120:123], v[144:147], v[204:207], v[120:123]
	v_mfma_f32_16x16x32_bf16 v[116:119], v[148:151], v[204:207], v[116:119]
	v_mfma_f32_16x16x32_bf16 v[112:115], v[154:157], v[204:207], v[112:115]
	s_waitcnt lgkmcnt(2)
	v_mfma_f32_16x16x32_bf16 v[108:111], v[128:131], v[208:211], v[108:111]
	ds_read_b128 v[204:207], v232 offset:8192
	v_mfma_f32_16x16x32_bf16 v[104:107], v[144:147], v[208:211], v[104:107]
	v_mfma_f32_16x16x32_bf16 v[100:103], v[148:151], v[208:211], v[100:103]
	v_mfma_f32_16x16x32_bf16 v[96:99], v[154:157], v[208:211], v[96:99]
	s_waitcnt lgkmcnt(2)
	v_mfma_f32_16x16x32_bf16 v[92:95], v[128:131], v[212:215], v[92:95]
	ds_read_b128 v[208:211], v232 offset:10240
	ds_read_b128 v[216:219], v153 offset:33792
	v_mfma_f32_16x16x32_bf16 v[88:91], v[144:147], v[212:215], v[88:91]
	v_mfma_f32_16x16x32_bf16 v[84:87], v[148:151], v[212:215], v[84:87]
	v_mfma_f32_16x16x32_bf16 v[80:83], v[154:157], v[212:215], v[80:83]
	s_waitcnt lgkmcnt(3)
	v_mfma_f32_16x16x32_bf16 v[76:79], v[128:131], v[240:243], v[76:79]
	ds_read_b128 v[212:215], v232 offset:12288
	ds_read_b128 v[220:223], v153 offset:35840
	v_mfma_f32_16x16x32_bf16 v[72:75], v[144:147], v[240:243], v[72:75]
	v_mfma_f32_16x16x32_bf16 v[68:71], v[148:151], v[240:243], v[68:71]
	v_mfma_f32_16x16x32_bf16 v[64:67], v[154:157], v[240:243], v[64:67]
	s_waitcnt lgkmcnt(4)
	v_mfma_f32_16x16x32_bf16 v[60:63], v[128:131], v[204:207], v[60:63]
	ds_read_b128 v[240:243], v232 offset:14336
	ds_read_b128 v[224:227], v153 offset:37888
	v_mfma_f32_16x16x32_bf16 v[56:59], v[144:147], v[204:207], v[56:59]
	v_mfma_f32_16x16x32_bf16 v[52:55], v[148:151], v[204:207], v[52:55]
	v_mfma_f32_16x16x32_bf16 v[48:51], v[154:157], v[204:207], v[48:51]
	s_waitcnt lgkmcnt(5)
	v_mfma_f32_16x16x32_bf16 v[44:47], v[128:131], v[208:211], v[44:47]
	ds_read_b128 v[204:207], v232 offset:1024
	ds_read_b128 v[228:231], v153 offset:39936
	v_mfma_f32_16x16x32_bf16 v[40:43], v[144:147], v[208:211], v[40:43]
	v_mfma_f32_16x16x32_bf16 v[36:39], v[148:151], v[208:211], v[36:39]
	v_mfma_f32_16x16x32_bf16 v[32:35], v[154:157], v[208:211], v[32:35]
	s_waitcnt lgkmcnt(5)
	v_mfma_f32_16x16x32_bf16 v[28:31], v[128:131], v[212:215], v[28:31]
	ds_read_b128 v[208:211], v232 offset:3072
	v_mfma_f32_16x16x32_bf16 v[24:27], v[144:147], v[212:215], v[24:27]
	v_mfma_f32_16x16x32_bf16 v[20:23], v[148:151], v[212:215], v[20:23]
	v_mfma_f32_16x16x32_bf16 v[16:19], v[154:157], v[212:215], v[16:19]
	s_waitcnt lgkmcnt(4)
	v_mfma_f32_16x16x32_bf16 v[12:15], v[128:131], v[240:243], v[12:15]
	ds_read_b128 v[212:215], v232 offset:5120
	v_mfma_f32_16x16x32_bf16 v[8:11], v[144:147], v[240:243], v[8:11]
	v_mfma_f32_16x16x32_bf16 v[4:7], v[148:151], v[240:243], v[4:7]
	v_mfma_f32_16x16x32_bf16 v[0:3], v[154:157], v[240:243], v[0:3]
	s_waitcnt lgkmcnt(2)
	v_mfma_f32_16x16x32_bf16 v[124:127], v[216:219], v[204:207], v[124:127]
	ds_read_b128 v[240:243], v232 offset:7168
	v_mfma_f32_16x16x32_bf16 v[120:123], v[220:223], v[204:207], v[120:123]
	v_mfma_f32_16x16x32_bf16 v[116:119], v[224:227], v[204:207], v[116:119]
	v_mfma_f32_16x16x32_bf16 v[112:115], v[228:231], v[204:207], v[112:115]
	s_waitcnt lgkmcnt(2)
	v_mfma_f32_16x16x32_bf16 v[108:111], v[216:219], v[208:211], v[108:111]
	ds_read_b128 v[204:207], v232 offset:9216
	v_mfma_f32_16x16x32_bf16 v[104:107], v[220:223], v[208:211], v[104:107]
	v_mfma_f32_16x16x32_bf16 v[100:103], v[224:227], v[208:211], v[100:103]
	v_mfma_f32_16x16x32_bf16 v[96:99], v[228:231], v[208:211], v[96:99]
	s_waitcnt lgkmcnt(2)
	v_mfma_f32_16x16x32_bf16 v[92:95], v[216:219], v[212:215], v[92:95]
	ds_read_b128 v[208:211], v232 offset:11264
	v_mfma_f32_16x16x32_bf16 v[88:91], v[220:223], v[212:215], v[88:91]
	v_mfma_f32_16x16x32_bf16 v[84:87], v[224:227], v[212:215], v[84:87]
	v_mfma_f32_16x16x32_bf16 v[80:83], v[228:231], v[212:215], v[80:83]
	s_waitcnt lgkmcnt(2)
	v_mfma_f32_16x16x32_bf16 v[76:79], v[216:219], v[240:243], v[76:79]
	ds_read_b128 v[212:215], v232 offset:13312
	v_mfma_f32_16x16x32_bf16 v[72:75], v[220:223], v[240:243], v[72:75]
	v_mfma_f32_16x16x32_bf16 v[68:71], v[224:227], v[240:243], v[68:71]
	v_mfma_f32_16x16x32_bf16 v[64:67], v[228:231], v[240:243], v[64:67]
	s_waitcnt lgkmcnt(2)
	v_mfma_f32_16x16x32_bf16 v[60:63], v[216:219], v[204:207], v[60:63]
	ds_read_b128 v[240:243], v232 offset:15360
	v_mfma_f32_16x16x32_bf16 v[56:59], v[220:223], v[204:207], v[56:59]
	v_mfma_f32_16x16x32_bf16 v[52:55], v[224:227], v[204:207], v[52:55]
	v_mfma_f32_16x16x32_bf16 v[48:51], v[228:231], v[204:207], v[48:51]
	s_waitcnt lgkmcnt(2)
	v_mfma_f32_16x16x32_bf16 v[44:47], v[216:219], v[208:211], v[44:47]
	v_mfma_f32_16x16x32_bf16 v[40:43], v[220:223], v[208:211], v[40:43]
	v_mfma_f32_16x16x32_bf16 v[36:39], v[224:227], v[208:211], v[36:39]
	v_mfma_f32_16x16x32_bf16 v[32:35], v[228:231], v[208:211], v[32:35]
	s_waitcnt lgkmcnt(1)
	v_mfma_f32_16x16x32_bf16 v[28:31], v[216:219], v[212:215], v[28:31]
	v_mfma_f32_16x16x32_bf16 v[24:27], v[220:223], v[212:215], v[24:27]
	v_mfma_f32_16x16x32_bf16 v[20:23], v[224:227], v[212:215], v[20:23]
	v_mfma_f32_16x16x32_bf16 v[16:19], v[228:231], v[212:215], v[16:19]
	s_waitcnt lgkmcnt(0)
	v_mfma_f32_16x16x32_bf16 v[12:15], v[216:219], v[240:243], v[12:15]
	v_mfma_f32_16x16x32_bf16 v[8:11], v[220:223], v[240:243], v[8:11]
	v_mfma_f32_16x16x32_bf16 v[4:7], v[224:227], v[240:243], v[4:7]
	v_mfma_f32_16x16x32_bf16 v[0:3], v[228:231], v[240:243], v[0:3]
	s_add_i32 s38, s38, 1
	s_addk_i32 s39, 0x80
	s_cmp_eq_u32 s65, s39
	s_cbranch_scc0 .LBB0_263

; __device__ __forceinline__ float erf_fast(float x) {
;   const float ax = fabsf(x);
;   const float t = __builtin_amdgcn_rcpf(fmaf(0.3275911f, ax, 1.0f));
;   float p = fmaf(1.061405429f, t, -1.453152027f);
;   p = fmaf(p, t, 1.421413741f); p = fmaf(p, t, -0.284496736f); p = fmaf(p, t, 0.254829592f);
;   const float e = 1.0f - p * t * __expf(-ax * ax);
;   return copysignf(e, x);
; }
; template <int MODE> __device__ __forceinline__ void epi_store(const GemmDesc& g, int row, int col, f32x4 v) {
;     ...
;     case E_GELU: {
;       const float4 bb = *(const float4*)(g.b0 + col);
;       float t[4] = {v[0] + bb.x, v[1] + bb.y, v[2] + bb.z, v[3] + bb.w};
; #pragma unroll
;       for (int i = 0; i < 4; ++i) t[i] = 0.5f * t[i] * (1.0f + erf_fast(t[i] * 0.70710678118654752f));
;       uint2 o; o.x = pack2(t[0], t[1]); o.y = pack2(t[2], t[3]);
;       *(uint2*)((u16*)g.o0 + (size_t)row * g.ldo + col) = o;
;     } break;
.LBB0_1029:
	s_and_b64 vcc, exec, s[4:5]
	s_cbranch_vccz .LBB0_1031
	v_or_b32_e32 v204, s38, v175
	v_lshlrev_b32_e32 v204, 2, v204
	global_load_dwordx4 v[220:223], v204, s[12:13]
	global_load_dwordx4 v[224:227], v204, s[12:13] offset:64
	global_load_dwordx4 v[228:231], v204, s[12:13] offset:128
	global_load_dwordx4 v[232:235], v204, s[12:13] offset:192
	v_mov_b32_e32 v244, 0xbfba00e3
	v_mov_b32_e32 v245, 0xbfba00e3
	v_and_b32_e32 v204, 63, v135
	v_and_b32_e32 v205, 15, v204
	v_lshrrev_b32_e32 v206, 4, v204
	v_lshrrev_b32_e32 v207, 3, v204
	v_and_b32_e32 v208, 7, v204
	v_lshrrev_b32_e32 v209, 8, v135
	v_bfe_u32 v210, v135, 6, 2
	v_lshrrev_b32_e32 v211, 6, v135
	v_lshlrev_b32_e32 v211, 11, v211
	v_add_u32_e32 v211, 0x20000, v211
	v_lshrrev_b32_e32 v212, 1, v206
	v_and_b32_e32 v213, 7, v205
	v_xor_b32_e32 v212, v212, v213
	v_lshlrev_b32_e32 v212, 4, v212
	v_and_b32_e32 v213, 1, v206
	v_lshl_add_u32 v212, v213, 3, v212
	v_lshl_add_u32 v212, v205, 7, v212
	v_add_u32_e32 v148, v211, v212
	v_xor_b32_e32 v149, 32, v148
	v_xor_b32_e32 v150, 64, v148
	v_xor_b32_e32 v151, 0x60, v148
	v_xor_b32_e32 v212, v208, v207
	v_lshlrev_b32_e32 v212, 4, v212
	v_lshl_add_u32 v212, v207, 7, v212
	v_add_u32_e32 v156, v211, v212
	v_lshl_add_u32 v212, v209, 7, v207
	v_add_u32_e32 v212, s39, v212
	v_lshlrev_b32_e32 v213, 3, v208
	v_lshl_add_u32 v213, v210, 6, v213
	v_add_u32_e32 v213, s38, v213
	v_mul_lo_u32 v212, v212, s94
	v_add_lshl_u32 v146, v212, v213, 1
	s_lshl_b32 s4, s94, 4
	s_lshl_b32 s5, s94, 5
	v_add_u32_e32 v147, s4, v146
	s_waitcnt vmcnt(0)
	v_pk_add_f32 v[204:205], v[124:125], v[220:221]
	v_pk_add_f32 v[214:215], v[126:127], v[222:223]
	v_pk_mul_f32 v[206:207], v[204:205], 0.5 op_sel_hi:[1,0]
	v_pk_mul_f32 v[216:217], v[214:215], 0.5 op_sel_hi:[1,0]
	v_pk_mul_f32 v[204:205], v[204:205], s[50:51] op_sel_hi:[1,0]
	v_pk_mul_f32 v[214:215], v[214:215], s[50:51] op_sel_hi:[1,0]
	v_mul_f32_e64 v208, |v204|, -|v204|
	v_mul_f32_e64 v218, |v214|, -|v214|
	v_mul_f32_e64 v209, |v205|, -|v205|
	v_mul_f32_e64 v219, |v215|, -|v215|
	v_fma_f32 v210, |v204|, s78, 1.0
	v_fma_f32 v128, |v214|, s78, 1.0
	v_fma_f32 v211, |v205|, s78, 1.0
	v_fma_f32 v129, |v215|, s78, 1.0
	v_mul_f32_e32 v208, 0x3fb8aa3b, v208
	v_mul_f32_e32 v218, 0x3fb8aa3b, v218
	v_mul_f32_e32 v209, 0x3fb8aa3b, v209
	v_mul_f32_e32 v219, 0x3fb8aa3b, v219
	v_rcp_f32_e32 v210, v210
	v_rcp_f32_e32 v128, v128
	v_rcp_f32_e32 v211, v211
	v_rcp_f32_e32 v129, v129
	v_exp_f32_e32 v208, v208
	v_exp_f32_e32 v218, v218
	v_exp_f32_e32 v209, v209
	v_exp_f32_e32 v219, v219
	v_pk_fma_f32 v[212:213], v[210:211], s[86:87], v[244:245] op_sel_hi:[1,0,1]
	v_pk_fma_f32 v[130:131], v[128:129], s[86:87], v[244:245] op_sel_hi:[1,0,1]
	v_pk_fma_f32 v[212:213], v[212:213], v[210:211], s[88:89] op_sel_hi:[1,1,0]
	v_pk_fma_f32 v[130:131], v[130:131], v[128:129], s[88:89] op_sel_hi:[1,1,0]
	v_pk_fma_f32 v[212:213], v[212:213], v[210:211], s[90:91] op_sel_hi:[1,1,0]
	v_pk_fma_f32 v[130:131], v[130:131], v[128:129], s[90:91] op_sel_hi:[1,1,0]
	v_pk_fma_f32 v[212:213], v[212:213], v[210:211], s[96:97] op_sel_hi:[1,1,0]
	v_pk_fma_f32 v[130:131], v[130:131], v[128:129], s[96:97] op_sel_hi:[1,1,0]
	v_pk_mul_f32 v[212:213], v[210:211], v[212:213]
	v_pk_mul_f32 v[130:131], v[128:129], v[130:131]
	v_pk_fma_f32 v[212:213], v[208:209], v[212:213], 1.0 op_sel_hi:[1,1,0] neg_lo:[1,0,0] neg_hi:[1,0,0]
	v_pk_fma_f32 v[130:131], v[218:219], v[130:131], 1.0 op_sel_hi:[1,1,0] neg_lo:[1,0,0] neg_hi:[1,0,0]
	v_bfi_b32 v204, s35, v212, v204
	v_bfi_b32 v214, s35, v130, v214
	v_bfi_b32 v205, s35, v213, v205
	v_bfi_b32 v215, s35, v131, v215
	v_pk_add_f32 v[204:205], v[204:205], 1.0 op_sel_hi:[1,0]
	v_pk_add_f32 v[214:215], v[214:215], 1.0 op_sel_hi:[1,0]
	v_pk_mul_f32 v[206:207], v[206:207], v[204:205]
	v_pk_mul_f32 v[216:217], v[216:217], v[214:215]
	v_cvt_pk_bf16_f32 v152, v206, v207
	v_cvt_pk_bf16_f32 v153, v216, v217
	ds_write_b64 v148, v[152:153]
	v_pk_add_f32 v[204:205], v[120:121], v[224:225]
	v_pk_add_f32 v[214:215], v[122:123], v[226:227]
	v_pk_mul_f32 v[206:207], v[204:205], 0.5 op_sel_hi:[1,0]
	v_pk_mul_f32 v[216:217], v[214:215], 0.5 op_sel_hi:[1,0]
	v_pk_mul_f32 v[204:205], v[204:205], s[50:51] op_sel_hi:[1,0]
	v_pk_mul_f32 v[214:215], v[214:215], s[50:51] op_sel_hi:[1,0]
	v_mul_f32_e64 v208, |v204|, -|v204|
	v_mul_f32_e64 v218, |v214|, -|v214|
	v_mul_f32_e64 v209, |v205|, -|v205|
	v_mul_f32_e64 v219, |v215|, -|v215|
	v_fma_f32 v210, |v204|, s78, 1.0
	v_fma_f32 v128, |v214|, s78, 1.0
	v_fma_f32 v211, |v205|, s78, 1.0
	v_fma_f32 v129, |v215|, s78, 1.0
	v_mul_f32_e32 v208, 0x3fb8aa3b, v208
	v_mul_f32_e32 v218, 0x3fb8aa3b, v218
	v_mul_f32_e32 v209, 0x3fb8aa3b, v209
	v_mul_f32_e32 v219, 0x3fb8aa3b, v219
	v_rcp_f32_e32 v210, v210
	v_rcp_f32_e32 v128, v128
	v_rcp_f32_e32 v211, v211
	v_rcp_f32_e32 v129, v129
	v_exp_f32_e32 v208, v208
	v_exp_f32_e32 v218, v218
	v_exp_f32_e32 v209, v209
	v_exp_f32_e32 v219, v219
	v_pk_fma_f32 v[212:213], v[210:211], s[86:87], v[244:245] op_sel_hi:[1,0,1]
	v_pk_fma_f32 v[130:131], v[128:129], s[86:87], v[244:245] op_sel_hi:[1,0,1]
	v_pk_fma_f32 v[212:213], v[212:213], v[210:211], s[88:89] op_sel_hi:[1,1,0]
	v_pk_fma_f32 v[130:131], v[130:131], v[128:129], s[88:89] op_sel_hi:[1,1,0]
	v_pk_fma_f32 v[212:213], v[212:213], v[210:211], s[90:91] op_sel_hi:[1,1,0]
	v_pk_fma_f32 v[130:131], v[130:131], v[128:129], s[90:91] op_sel_hi:[1,1,0]
	v_pk_fma_f32 v[212:213], v[212:213], v[210:211], s[96:97] op_sel_hi:[1,1,0]
	v_pk_fma_f32 v[130:131], v[130:131], v[128:129], s[96:97] op_sel_hi:[1,1,0]
	v_pk_mul_f32 v[212:213], v[210:211], v[212:213]
	v_pk_mul_f32 v[130:131], v[128:129], v[130:131]
; __device__ __forceinline__ float erf_fast(float x) {
;   const float ax = fabsf(x);
;   const float t = __builtin_amdgcn_rcpf(fmaf(0.3275911f, ax, 1.0f));
;   float p = fmaf(1.061405429f, t, -1.453152027f);
;   p = fmaf(p, t, 1.421413741f); p = fmaf(p, t, -0.284496736f); p = fmaf(p, t, 0.254829592f);
;   const float e = 1.0f - p * t * __expf(-ax * ax);
;   return copysignf(e, x);
; }
; template <int MODE> __device__ __forceinline__ void epi_store(const GemmDesc& g, int row, int col, f32x4 v) {
;     ...
;     case E_GELU: {
;       const float4 bb = *(const float4*)(g.b0 + col);
;       float t[4] = {v[0] + bb.x, v[1] + bb.y, v[2] + bb.z, v[3] + bb.w};
; #pragma unroll
;       for (int i = 0; i < 4; ++i) t[i] = 0.5f * t[i] * (1.0f + erf_fast(t[i] * 0.70710678118654752f));
;       uint2 o; o.x = pack2(t[0], t[1]); o.y = pack2(t[2], t[3]);
;       *(uint2*)((u16*)g.o0 + (size_t)row * g.ldo + col) = o;
;     } break;
	v_pk_fma_f32 v[212:213], v[208:209], v[212:213], 1.0 op_sel_hi:[1,1,0] neg_lo:[1,0,0] neg_hi:[1,0,0]
	v_pk_fma_f32 v[130:131], v[218:219], v[130:131], 1.0 op_sel_hi:[1,1,0] neg_lo:[1,0,0] neg_hi:[1,0,0]
	v_bfi_b32 v204, s35, v212, v204
	v_bfi_b32 v214, s35, v130, v214
	v_bfi_b32 v205, s35, v213, v205
	v_bfi_b32 v215, s35, v131, v215
	v_pk_add_f32 v[204:205], v[204:205], 1.0 op_sel_hi:[1,0]
	v_pk_add_f32 v[214:215], v[214:215], 1.0 op_sel_hi:[1,0]
	v_pk_mul_f32 v[206:207], v[206:207], v[204:205]
	v_pk_mul_f32 v[216:217], v[216:217], v[214:215]
	v_cvt_pk_bf16_f32 v154, v206, v207
	v_cvt_pk_bf16_f32 v155, v216, v217
	ds_write_b64 v149, v[154:155]
	v_pk_add_f32 v[204:205], v[116:117], v[228:229]
	v_pk_add_f32 v[214:215], v[118:119], v[230:231]
	v_pk_mul_f32 v[206:207], v[204:205], 0.5 op_sel_hi:[1,0]
	v_pk_mul_f32 v[216:217], v[214:215], 0.5 op_sel_hi:[1,0]
	v_pk_mul_f32 v[204:205], v[204:205], s[50:51] op_sel_hi:[1,0]
	v_pk_mul_f32 v[214:215], v[214:215], s[50:51] op_sel_hi:[1,0]
	v_mul_f32_e64 v208, |v204|, -|v204|
	v_mul_f32_e64 v218, |v214|, -|v214|
	v_mul_f32_e64 v209, |v205|, -|v205|
	v_mul_f32_e64 v219, |v215|, -|v215|
	v_fma_f32 v210, |v204|, s78, 1.0
	v_fma_f32 v128, |v214|, s78, 1.0
	v_fma_f32 v211, |v205|, s78, 1.0
	v_fma_f32 v129, |v215|, s78, 1.0
	v_mul_f32_e32 v208, 0x3fb8aa3b, v208
	v_mul_f32_e32 v218, 0x3fb8aa3b, v218
	v_mul_f32_e32 v209, 0x3fb8aa3b, v209
	v_mul_f32_e32 v219, 0x3fb8aa3b, v219
	v_rcp_f32_e32 v210, v210
	v_rcp_f32_e32 v128, v128
	v_rcp_f32_e32 v211, v211
	v_rcp_f32_e32 v129, v129
	v_exp_f32_e32 v208, v208
	v_exp_f32_e32 v218, v218
	v_exp_f32_e32 v209, v209
	v_exp_f32_e32 v219, v219
	v_pk_fma_f32 v[212:213], v[210:211], s[86:87], v[244:245] op_sel_hi:[1,0,1]
	v_pk_fma_f32 v[130:131], v[128:129], s[86:87], v[244:245] op_sel_hi:[1,0,1]
	v_pk_fma_f32 v[212:213], v[212:213], v[210:211], s[88:89] op_sel_hi:[1,1,0]
	v_pk_fma_f32 v[130:131], v[130:131], v[128:129], s[88:89] op_sel_hi:[1,1,0]
	v_pk_fma_f32 v[212:213], v[212:213], v[210:211], s[90:91] op_sel_hi:[1,1,0]
	v_pk_fma_f32 v[130:131], v[130:131], v[128:129], s[90:91] op_sel_hi:[1,1,0]
	v_pk_fma_f32 v[212:213], v[212:213], v[210:211], s[96:97] op_sel_hi:[1,1,0]
	v_pk_fma_f32 v[130:131], v[130:131], v[128:129], s[96:97] op_sel_hi:[1,1,0]
	v_pk_mul_f32 v[212:213], v[210:211], v[212:213]
	v_pk_mul_f32 v[130:131], v[128:129], v[130:131]
	v_pk_fma_f32 v[212:213], v[208:209], v[212:213], 1.0 op_sel_hi:[1,1,0] neg_lo:[1,0,0] neg_hi:[1,0,0]
	v_pk_fma_f32 v[130:131], v[218:219], v[130:131], 1.0 op_sel_hi:[1,1,0] neg_lo:[1,0,0] neg_hi:[1,0,0]
	v_bfi_b32 v204, s35, v212, v204
	v_bfi_b32 v214, s35, v130, v214
	v_bfi_b32 v205, s35, v213, v205
	v_bfi_b32 v215, s35, v131, v215
	v_pk_add_f32 v[204:205], v[204:205], 1.0 op_sel_hi:[1,0]
	v_pk_add_f32 v[214:215], v[214:215], 1.0 op_sel_hi:[1,0]
	v_pk_mul_f32 v[206:207], v[206:207], v[204:205]
	v_pk_mul_f32 v[216:217], v[216:217], v[214:215]
	v_cvt_pk_bf16_f32 v152, v206, v207
	v_cvt_pk_bf16_f32 v153, v216, v217
	ds_write_b64 v150, v[152:153]
	v_pk_add_f32 v[204:205], v[112:113], v[232:233]
	v_pk_add_f32 v[214:215], v[114:115], v[234:235]
	v_pk_mul_f32 v[206:207], v[204:205], 0.5 op_sel_hi:[1,0]
	v_pk_mul_f32 v[216:217], v[214:215], 0.5 op_sel_hi:[1,0]
	v_pk_mul_f32 v[204:205], v[204:205], s[50:51] op_sel_hi:[1,0]
	v_pk_mul_f32 v[214:215], v[214:215], s[50:51] op_sel_hi:[1,0]
	v_mul_f32_e64 v208, |v204|, -|v204|
	v_mul_f32_e64 v218, |v214|, -|v214|
	v_mul_f32_e64 v209, |v205|, -|v205|
	v_mul_f32_e64 v219, |v215|, -|v215|
	v_fma_f32 v210, |v204|, s78, 1.0
	v_fma_f32 v128, |v214|, s78, 1.0
	v_fma_f32 v211, |v205|, s78, 1.0
	v_fma_f32 v129, |v215|, s78, 1.0
	v_mul_f32_e32 v208, 0x3fb8aa3b, v208
	v_mul_f32_e32 v218, 0x3fb8aa3b, v218
	v_mul_f32_e32 v209, 0x3fb8aa3b, v209
	v_mul_f32_e32 v219, 0x3fb8aa3b, v219
	v_rcp_f32_e32 v210, v210
	v_rcp_f32_e32 v128, v128
	v_rcp_f32_e32 v211, v211
	v_rcp_f32_e32 v129, v129
	v_exp_f32_e32 v208, v208
	v_exp_f32_e32 v218, v218
	v_exp_f32_e32 v209, v209
	v_exp_f32_e32 v219, v219
	v_pk_fma_f32 v[212:213], v[210:211], s[86:87], v[244:245] op_sel_hi:[1,0,1]
	v_pk_fma_f32 v[130:131], v[128:129], s[86:87], v[244:245] op_sel_hi:[1,0,1]
	v_pk_fma_f32 v[212:213], v[212:213], v[210:211], s[88:89] op_sel_hi:[1,1,0]
	v_pk_fma_f32 v[130:131], v[130:131], v[128:129], s[88:89] op_sel_hi:[1,1,0]
	v_pk_fma_f32 v[212:213], v[212:213], v[210:211], s[90:91] op_sel_hi:[1,1,0]
	v_pk_fma_f32 v[130:131], v[130:131], v[128:129], s[90:91] op_sel_hi:[1,1,0]
	v_pk_fma_f32 v[212:213], v[212:213], v[210:211], s[96:97] op_sel_hi:[1,1,0]
	v_pk_fma_f32 v[130:131], v[130:131], v[128:129], s[96:97] op_sel_hi:[1,1,0]
	v_pk_mul_f32 v[212:213], v[210:211], v[212:213]
	v_pk_mul_f32 v[130:131], v[128:129], v[130:131]
	v_pk_fma_f32 v[212:213], v[208:209], v[212:213], 1.0 op_sel_hi:[1,1,0] neg_lo:[1,0,0] neg_hi:[1,0,0]
	v_pk_fma_f32 v[130:131], v[218:219], v[130:131], 1.0 op_sel_hi:[1,1,0] neg_lo:[1,0,0] neg_hi:[1,0,0]
	v_bfi_b32 v204, s35, v212, v204
	v_bfi_b32 v214, s35, v130, v214
	v_bfi_b32 v205, s35, v213, v205
	v_bfi_b32 v215, s35, v131, v215
	v_pk_add_f32 v[204:205], v[204:205], 1.0 op_sel_hi:[1,0]
	v_pk_add_f32 v[214:215], v[214:215], 1.0 op_sel_hi:[1,0]
	v_pk_mul_f32 v[206:207], v[206:207], v[204:205]
	v_pk_mul_f32 v[216:217], v[216:217], v[214:215]
	v_cvt_pk_bf16_f32 v154, v206, v207
	v_cvt_pk_bf16_f32 v155, v216, v217
	ds_write_b64 v151, v[154:155]
	ds_read_b128 v[236:239], v156
	ds_read_b128 v[240:243], v156 offset:1024
	v_pk_add_f32 v[204:205], v[108:109], v[220:221]
	v_pk_add_f32 v[214:215], v[110:111], v[222:223]
	v_pk_mul_f32 v[206:207], v[204:205], 0.5 op_sel_hi:[1,0]
	v_pk_mul_f32 v[216:217], v[214:215], 0.5 op_sel_hi:[1,0]
; __device__ __forceinline__ float erf_fast(float x) {
;   const float ax = fabsf(x);
;   const float t = __builtin_amdgcn_rcpf(fmaf(0.3275911f, ax, 1.0f));
;   float p = fmaf(1.061405429f, t, -1.453152027f);
;   p = fmaf(p, t, 1.421413741f); p = fmaf(p, t, -0.284496736f); p = fmaf(p, t, 0.254829592f);
;   const float e = 1.0f - p * t * __expf(-ax * ax);
;   return copysignf(e, x);
; }
; template <int MODE> __device__ __forceinline__ void epi_store(const GemmDesc& g, int row, int col, f32x4 v) {
;     ...
;     case E_GELU: {
;       const float4 bb = *(const float4*)(g.b0 + col);
;       float t[4] = {v[0] + bb.x, v[1] + bb.y, v[2] + bb.z, v[3] + bb.w};
; #pragma unroll
;       for (int i = 0; i < 4; ++i) t[i] = 0.5f * t[i] * (1.0f + erf_fast(t[i] * 0.70710678118654752f));
;       uint2 o; o.x = pack2(t[0], t[1]); o.y = pack2(t[2], t[3]);
;       *(uint2*)((u16*)g.o0 + (size_t)row * g.ldo + col) = o;
;     } break;
	v_pk_mul_f32 v[204:205], v[204:205], s[50:51] op_sel_hi:[1,0]
	v_pk_mul_f32 v[214:215], v[214:215], s[50:51] op_sel_hi:[1,0]
	v_mul_f32_e64 v208, |v204|, -|v204|
	v_mul_f32_e64 v218, |v214|, -|v214|
	v_mul_f32_e64 v209, |v205|, -|v205|
	v_mul_f32_e64 v219, |v215|, -|v215|
	v_fma_f32 v210, |v204|, s78, 1.0
	v_fma_f32 v128, |v214|, s78, 1.0
	v_fma_f32 v211, |v205|, s78, 1.0
	v_fma_f32 v129, |v215|, s78, 1.0
	v_mul_f32_e32 v208, 0x3fb8aa3b, v208
	v_mul_f32_e32 v218, 0x3fb8aa3b, v218
	v_mul_f32_e32 v209, 0x3fb8aa3b, v209
	v_mul_f32_e32 v219, 0x3fb8aa3b, v219
	v_rcp_f32_e32 v210, v210
	v_rcp_f32_e32 v128, v128
	v_rcp_f32_e32 v211, v211
	v_rcp_f32_e32 v129, v129
	v_exp_f32_e32 v208, v208
	v_exp_f32_e32 v218, v218
	v_exp_f32_e32 v209, v209
	v_exp_f32_e32 v219, v219
	v_pk_fma_f32 v[212:213], v[210:211], s[86:87], v[244:245] op_sel_hi:[1,0,1]
	v_pk_fma_f32 v[130:131], v[128:129], s[86:87], v[244:245] op_sel_hi:[1,0,1]
	v_pk_fma_f32 v[212:213], v[212:213], v[210:211], s[88:89] op_sel_hi:[1,1,0]
	v_pk_fma_f32 v[130:131], v[130:131], v[128:129], s[88:89] op_sel_hi:[1,1,0]
	v_pk_fma_f32 v[212:213], v[212:213], v[210:211], s[90:91] op_sel_hi:[1,1,0]
	v_pk_fma_f32 v[130:131], v[130:131], v[128:129], s[90:91] op_sel_hi:[1,1,0]
	v_pk_fma_f32 v[212:213], v[212:213], v[210:211], s[96:97] op_sel_hi:[1,1,0]
	v_pk_fma_f32 v[130:131], v[130:131], v[128:129], s[96:97] op_sel_hi:[1,1,0]
	v_pk_mul_f32 v[212:213], v[210:211], v[212:213]
	v_pk_mul_f32 v[130:131], v[128:129], v[130:131]
	v_pk_fma_f32 v[212:213], v[208:209], v[212:213], 1.0 op_sel_hi:[1,1,0] neg_lo:[1,0,0] neg_hi:[1,0,0]
	v_pk_fma_f32 v[130:131], v[218:219], v[130:131], 1.0 op_sel_hi:[1,1,0] neg_lo:[1,0,0] neg_hi:[1,0,0]
	v_bfi_b32 v204, s35, v212, v204
	v_bfi_b32 v214, s35, v130, v214
	v_bfi_b32 v205, s35, v213, v205
	v_bfi_b32 v215, s35, v131, v215
	v_pk_add_f32 v[204:205], v[204:205], 1.0 op_sel_hi:[1,0]
	v_pk_add_f32 v[214:215], v[214:215], 1.0 op_sel_hi:[1,0]
	v_pk_mul_f32 v[206:207], v[206:207], v[204:205]
	v_pk_mul_f32 v[216:217], v[216:217], v[214:215]
	v_cvt_pk_bf16_f32 v152, v206, v207
	v_cvt_pk_bf16_f32 v153, v216, v217
	ds_write_b64 v148, v[152:153]
	v_pk_add_f32 v[204:205], v[104:105], v[224:225]
	v_pk_add_f32 v[214:215], v[106:107], v[226:227]
	v_pk_mul_f32 v[206:207], v[204:205], 0.5 op_sel_hi:[1,0]
	v_pk_mul_f32 v[216:217], v[214:215], 0.5 op_sel_hi:[1,0]
	v_pk_mul_f32 v[204:205], v[204:205], s[50:51] op_sel_hi:[1,0]
	v_pk_mul_f32 v[214:215], v[214:215], s[50:51] op_sel_hi:[1,0]
	v_mul_f32_e64 v208, |v204|, -|v204|
	v_mul_f32_e64 v218, |v214|, -|v214|
	v_mul_f32_e64 v209, |v205|, -|v205|
	v_mul_f32_e64 v219, |v215|, -|v215|
	v_fma_f32 v210, |v204|, s78, 1.0
	v_fma_f32 v128, |v214|, s78, 1.0
	v_fma_f32 v211, |v205|, s78, 1.0
	v_fma_f32 v129, |v215|, s78, 1.0
	v_mul_f32_e32 v208, 0x3fb8aa3b, v208
	v_mul_f32_e32 v218, 0x3fb8aa3b, v218
	v_mul_f32_e32 v209, 0x3fb8aa3b, v209
	v_mul_f32_e32 v219, 0x3fb8aa3b, v219
	v_rcp_f32_e32 v210, v210
	v_rcp_f32_e32 v128, v128
	v_rcp_f32_e32 v211, v211
	v_rcp_f32_e32 v129, v129
	v_exp_f32_e32 v208, v208
	v_exp_f32_e32 v218, v218
	v_exp_f32_e32 v209, v209
	v_exp_f32_e32 v219, v219
	v_pk_fma_f32 v[212:213], v[210:211], s[86:87], v[244:245] op_sel_hi:[1,0,1]
	v_pk_fma_f32 v[130:131], v[128:129], s[86:87], v[244:245] op_sel_hi:[1,0,1]
	v_pk_fma_f32 v[212:213], v[212:213], v[210:211], s[88:89] op_sel_hi:[1,1,0]
	v_pk_fma_f32 v[130:131], v[130:131], v[128:129], s[88:89] op_sel_hi:[1,1,0]
	v_pk_fma_f32 v[212:213], v[212:213], v[210:211], s[90:91] op_sel_hi:[1,1,0]
	v_pk_fma_f32 v[130:131], v[130:131], v[128:129], s[90:91] op_sel_hi:[1,1,0]
	v_pk_fma_f32 v[212:213], v[212:213], v[210:211], s[96:97] op_sel_hi:[1,1,0]
	v_pk_fma_f32 v[130:131], v[130:131], v[128:129], s[96:97] op_sel_hi:[1,1,0]
	v_pk_mul_f32 v[212:213], v[210:211], v[212:213]
	v_pk_mul_f32 v[130:131], v[128:129], v[130:131]
	v_pk_fma_f32 v[212:213], v[208:209], v[212:213], 1.0 op_sel_hi:[1,1,0] neg_lo:[1,0,0] neg_hi:[1,0,0]
	v_pk_fma_f32 v[130:131], v[218:219], v[130:131], 1.0 op_sel_hi:[1,1,0] neg_lo:[1,0,0] neg_hi:[1,0,0]
	v_bfi_b32 v204, s35, v212, v204
	v_bfi_b32 v214, s35, v130, v214
	v_bfi_b32 v205, s35, v213, v205
	v_bfi_b32 v215, s35, v131, v215
	v_pk_add_f32 v[204:205], v[204:205], 1.0 op_sel_hi:[1,0]
	v_pk_add_f32 v[214:215], v[214:215], 1.0 op_sel_hi:[1,0]
	v_pk_mul_f32 v[206:207], v[206:207], v[204:205]
	v_pk_mul_f32 v[216:217], v[216:217], v[214:215]
	v_cvt_pk_bf16_f32 v154, v206, v207
	v_cvt_pk_bf16_f32 v155, v216, v217
	ds_write_b64 v149, v[154:155]
	v_pk_add_f32 v[204:205], v[100:101], v[228:229]
	v_pk_add_f32 v[214:215], v[102:103], v[230:231]
	v_pk_mul_f32 v[206:207], v[204:205], 0.5 op_sel_hi:[1,0]
	v_pk_mul_f32 v[216:217], v[214:215], 0.5 op_sel_hi:[1,0]
	v_pk_mul_f32 v[204:205], v[204:205], s[50:51] op_sel_hi:[1,0]
	v_pk_mul_f32 v[214:215], v[214:215], s[50:51] op_sel_hi:[1,0]
	v_mul_f32_e64 v208, |v204|, -|v204|
	v_mul_f32_e64 v218, |v214|, -|v214|
	v_mul_f32_e64 v209, |v205|, -|v205|
	v_mul_f32_e64 v219, |v215|, -|v215|
	v_fma_f32 v210, |v204|, s78, 1.0
	v_fma_f32 v128, |v214|, s78, 1.0
	v_fma_f32 v211, |v205|, s78, 1.0
	v_fma_f32 v129, |v215|, s78, 1.0
	v_mul_f32_e32 v208, 0x3fb8aa3b, v208
	v_mul_f32_e32 v218, 0x3fb8aa3b, v218
	v_mul_f32_e32 v209, 0x3fb8aa3b, v209
	v_mul_f32_e32 v219, 0x3fb8aa3b, v219
	v_rcp_f32_e32 v210, v210
	v_rcp_f32_e32 v128, v128
	v_rcp_f32_e32 v211, v211
	v_rcp_f32_e32 v129, v129
	v_exp_f32_e32 v208, v208
	v_exp_f32_e32 v218, v218
	v_exp_f32_e32 v209, v209
	v_exp_f32_e32 v219, v219
	v_pk_fma_f32 v[212:213], v[210:211], s[86:87], v[244:245] op_sel_hi:[1,0,1]
	v_pk_fma_f32 v[130:131], v[128:129], s[86:87], v[244:245] op_sel_hi:[1,0,1]
; __device__ __forceinline__ float erf_fast(float x) {
;   const float ax = fabsf(x);
;   const float t = __builtin_amdgcn_rcpf(fmaf(0.3275911f, ax, 1.0f));
;   float p = fmaf(1.061405429f, t, -1.453152027f);
;   p = fmaf(p, t, 1.421413741f); p = fmaf(p, t, -0.284496736f); p = fmaf(p, t, 0.254829592f);
;   const float e = 1.0f - p * t * __expf(-ax * ax);
;   return copysignf(e, x);
; }
; template <int MODE> __device__ __forceinline__ void epi_store(const GemmDesc& g, int row, int col, f32x4 v) {
;     ...
;     case E_GELU: {
;       const float4 bb = *(const float4*)(g.b0 + col);
;       float t[4] = {v[0] + bb.x, v[1] + bb.y, v[2] + bb.z, v[3] + bb.w};
; #pragma unroll
;       for (int i = 0; i < 4; ++i) t[i] = 0.5f * t[i] * (1.0f + erf_fast(t[i] * 0.70710678118654752f));
;       uint2 o; o.x = pack2(t[0], t[1]); o.y = pack2(t[2], t[3]);
;       *(uint2*)((u16*)g.o0 + (size_t)row * g.ldo + col) = o;
;     } break;
	v_pk_fma_f32 v[212:213], v[212:213], v[210:211], s[88:89] op_sel_hi:[1,1,0]
	v_pk_fma_f32 v[130:131], v[130:131], v[128:129], s[88:89] op_sel_hi:[1,1,0]
	v_pk_fma_f32 v[212:213], v[212:213], v[210:211], s[90:91] op_sel_hi:[1,1,0]
	v_pk_fma_f32 v[130:131], v[130:131], v[128:129], s[90:91] op_sel_hi:[1,1,0]
	v_pk_fma_f32 v[212:213], v[212:213], v[210:211], s[96:97] op_sel_hi:[1,1,0]
	v_pk_fma_f32 v[130:131], v[130:131], v[128:129], s[96:97] op_sel_hi:[1,1,0]
	v_pk_mul_f32 v[212:213], v[210:211], v[212:213]
	v_pk_mul_f32 v[130:131], v[128:129], v[130:131]
	v_pk_fma_f32 v[212:213], v[208:209], v[212:213], 1.0 op_sel_hi:[1,1,0] neg_lo:[1,0,0] neg_hi:[1,0,0]
	v_pk_fma_f32 v[130:131], v[218:219], v[130:131], 1.0 op_sel_hi:[1,1,0] neg_lo:[1,0,0] neg_hi:[1,0,0]
	v_bfi_b32 v204, s35, v212, v204
	v_bfi_b32 v214, s35, v130, v214
	v_bfi_b32 v205, s35, v213, v205
	v_bfi_b32 v215, s35, v131, v215
	v_pk_add_f32 v[204:205], v[204:205], 1.0 op_sel_hi:[1,0]
	v_pk_add_f32 v[214:215], v[214:215], 1.0 op_sel_hi:[1,0]
	v_pk_mul_f32 v[206:207], v[206:207], v[204:205]
	v_pk_mul_f32 v[216:217], v[216:217], v[214:215]
	v_cvt_pk_bf16_f32 v152, v206, v207
	v_cvt_pk_bf16_f32 v153, v216, v217
	ds_write_b64 v150, v[152:153]
	v_pk_add_f32 v[204:205], v[96:97], v[232:233]
	v_pk_add_f32 v[214:215], v[98:99], v[234:235]
	v_pk_mul_f32 v[206:207], v[204:205], 0.5 op_sel_hi:[1,0]
	v_pk_mul_f32 v[216:217], v[214:215], 0.5 op_sel_hi:[1,0]
	v_pk_mul_f32 v[204:205], v[204:205], s[50:51] op_sel_hi:[1,0]
	v_pk_mul_f32 v[214:215], v[214:215], s[50:51] op_sel_hi:[1,0]
	v_mul_f32_e64 v208, |v204|, -|v204|
	v_mul_f32_e64 v218, |v214|, -|v214|
	v_mul_f32_e64 v209, |v205|, -|v205|
	v_mul_f32_e64 v219, |v215|, -|v215|
	v_fma_f32 v210, |v204|, s78, 1.0
	v_fma_f32 v128, |v214|, s78, 1.0
	v_fma_f32 v211, |v205|, s78, 1.0
	v_fma_f32 v129, |v215|, s78, 1.0
	v_mul_f32_e32 v208, 0x3fb8aa3b, v208
	v_mul_f32_e32 v218, 0x3fb8aa3b, v218
	v_mul_f32_e32 v209, 0x3fb8aa3b, v209
	v_mul_f32_e32 v219, 0x3fb8aa3b, v219
	v_rcp_f32_e32 v210, v210
	v_rcp_f32_e32 v128, v128
	v_rcp_f32_e32 v211, v211
	v_rcp_f32_e32 v129, v129
	v_exp_f32_e32 v208, v208
	v_exp_f32_e32 v218, v218
	v_exp_f32_e32 v209, v209
	v_exp_f32_e32 v219, v219
	v_pk_fma_f32 v[212:213], v[210:211], s[86:87], v[244:245] op_sel_hi:[1,0,1]
	v_pk_fma_f32 v[130:131], v[128:129], s[86:87], v[244:245] op_sel_hi:[1,0,1]
	v_pk_fma_f32 v[212:213], v[212:213], v[210:211], s[88:89] op_sel_hi:[1,1,0]
	v_pk_fma_f32 v[130:131], v[130:131], v[128:129], s[88:89] op_sel_hi:[1,1,0]
	v_pk_fma_f32 v[212:213], v[212:213], v[210:211], s[90:91] op_sel_hi:[1,1,0]
	v_pk_fma_f32 v[130:131], v[130:131], v[128:129], s[90:91] op_sel_hi:[1,1,0]
	v_pk_fma_f32 v[212:213], v[212:213], v[210:211], s[96:97] op_sel_hi:[1,1,0]
	v_pk_fma_f32 v[130:131], v[130:131], v[128:129], s[96:97] op_sel_hi:[1,1,0]
	v_pk_mul_f32 v[212:213], v[210:211], v[212:213]
	v_pk_mul_f32 v[130:131], v[128:129], v[130:131]
	v_pk_fma_f32 v[212:213], v[208:209], v[212:213], 1.0 op_sel_hi:[1,1,0] neg_lo:[1,0,0] neg_hi:[1,0,0]
	v_pk_fma_f32 v[130:131], v[218:219], v[130:131], 1.0 op_sel_hi:[1,1,0] neg_lo:[1,0,0] neg_hi:[1,0,0]
	v_bfi_b32 v204, s35, v212, v204
	v_bfi_b32 v214, s35, v130, v214
	v_bfi_b32 v205, s35, v213, v205
	v_bfi_b32 v215, s35, v131, v215
	v_pk_add_f32 v[204:205], v[204:205], 1.0 op_sel_hi:[1,0]
	v_pk_add_f32 v[214:215], v[214:215], 1.0 op_sel_hi:[1,0]
	v_pk_mul_f32 v[206:207], v[206:207], v[204:205]
	v_pk_mul_f32 v[216:217], v[216:217], v[214:215]
	v_cvt_pk_bf16_f32 v154, v206, v207
	v_cvt_pk_bf16_f32 v155, v216, v217
	ds_write_b64 v151, v[154:155]
	s_waitcnt lgkmcnt(4)
	global_store_dwordx4 v146, v[236:239], s[66:67]
	global_store_dwordx4 v147, v[240:243], s[66:67]
	v_add_u32_e32 v146, s5, v146
	v_add_u32_e32 v147, s5, v147
	ds_read_b128 v[236:239], v156
	ds_read_b128 v[240:243], v156 offset:1024
	v_pk_add_f32 v[204:205], v[92:93], v[220:221]
	v_pk_add_f32 v[214:215], v[94:95], v[222:223]
	v_pk_mul_f32 v[206:207], v[204:205], 0.5 op_sel_hi:[1,0]
	v_pk_mul_f32 v[216:217], v[214:215], 0.5 op_sel_hi:[1,0]
	v_pk_mul_f32 v[204:205], v[204:205], s[50:51] op_sel_hi:[1,0]
	v_pk_mul_f32 v[214:215], v[214:215], s[50:51] op_sel_hi:[1,0]
	v_mul_f32_e64 v208, |v204|, -|v204|
	v_mul_f32_e64 v218, |v214|, -|v214|
	v_mul_f32_e64 v209, |v205|, -|v205|
	v_mul_f32_e64 v219, |v215|, -|v215|
	v_fma_f32 v210, |v204|, s78, 1.0
	v_fma_f32 v128, |v214|, s78, 1.0
	v_fma_f32 v211, |v205|, s78, 1.0
	v_fma_f32 v129, |v215|, s78, 1.0
	v_mul_f32_e32 v208, 0x3fb8aa3b, v208
	v_mul_f32_e32 v218, 0x3fb8aa3b, v218
	v_mul_f32_e32 v209, 0x3fb8aa3b, v209
	v_mul_f32_e32 v219, 0x3fb8aa3b, v219
	v_rcp_f32_e32 v210, v210
	v_rcp_f32_e32 v128, v128
	v_rcp_f32_e32 v211, v211
	v_rcp_f32_e32 v129, v129
	v_exp_f32_e32 v208, v208
	v_exp_f32_e32 v218, v218
	v_exp_f32_e32 v209, v209
	v_exp_f32_e32 v219, v219
	v_pk_fma_f32 v[212:213], v[210:211], s[86:87], v[244:245] op_sel_hi:[1,0,1]
	v_pk_fma_f32 v[130:131], v[128:129], s[86:87], v[244:245] op_sel_hi:[1,0,1]
	v_pk_fma_f32 v[212:213], v[212:213], v[210:211], s[88:89] op_sel_hi:[1,1,0]
	v_pk_fma_f32 v[130:131], v[130:131], v[128:129], s[88:89] op_sel_hi:[1,1,0]
	v_pk_fma_f32 v[212:213], v[212:213], v[210:211], s[90:91] op_sel_hi:[1,1,0]
	v_pk_fma_f32 v[130:131], v[130:131], v[128:129], s[90:91] op_sel_hi:[1,1,0]
	v_pk_fma_f32 v[212:213], v[212:213], v[210:211], s[96:97] op_sel_hi:[1,1,0]
	v_pk_fma_f32 v[130:131], v[130:131], v[128:129], s[96:97] op_sel_hi:[1,1,0]
	v_pk_mul_f32 v[212:213], v[210:211], v[212:213]
	v_pk_mul_f32 v[130:131], v[128:129], v[130:131]
	v_pk_fma_f32 v[212:213], v[208:209], v[212:213], 1.0 op_sel_hi:[1,1,0] neg_lo:[1,0,0] neg_hi:[1,0,0]
; __device__ __forceinline__ float erf_fast(float x) {
;   const float ax = fabsf(x);
;   const float t = __builtin_amdgcn_rcpf(fmaf(0.3275911f, ax, 1.0f));
;   float p = fmaf(1.061405429f, t, -1.453152027f);
;   p = fmaf(p, t, 1.421413741f); p = fmaf(p, t, -0.284496736f); p = fmaf(p, t, 0.254829592f);
;   const float e = 1.0f - p * t * __expf(-ax * ax);
;   return copysignf(e, x);
; }
; template <int MODE> __device__ __forceinline__ void epi_store(const GemmDesc& g, int row, int col, f32x4 v) {
;     ...
;     case E_GELU: {
;       const float4 bb = *(const float4*)(g.b0 + col);
;       float t[4] = {v[0] + bb.x, v[1] + bb.y, v[2] + bb.z, v[3] + bb.w};
; #pragma unroll
;       for (int i = 0; i < 4; ++i) t[i] = 0.5f * t[i] * (1.0f + erf_fast(t[i] * 0.70710678118654752f));
;       uint2 o; o.x = pack2(t[0], t[1]); o.y = pack2(t[2], t[3]);
;       *(uint2*)((u16*)g.o0 + (size_t)row * g.ldo + col) = o;
;     } break;
	v_pk_fma_f32 v[130:131], v[218:219], v[130:131], 1.0 op_sel_hi:[1,1,0] neg_lo:[1,0,0] neg_hi:[1,0,0]
	v_bfi_b32 v204, s35, v212, v204
	v_bfi_b32 v214, s35, v130, v214
	v_bfi_b32 v205, s35, v213, v205
	v_bfi_b32 v215, s35, v131, v215
	v_pk_add_f32 v[204:205], v[204:205], 1.0 op_sel_hi:[1,0]
	v_pk_add_f32 v[214:215], v[214:215], 1.0 op_sel_hi:[1,0]
	v_pk_mul_f32 v[206:207], v[206:207], v[204:205]
	v_pk_mul_f32 v[216:217], v[216:217], v[214:215]
	v_cvt_pk_bf16_f32 v152, v206, v207
	v_cvt_pk_bf16_f32 v153, v216, v217
	ds_write_b64 v148, v[152:153]
	v_pk_add_f32 v[204:205], v[88:89], v[224:225]
	v_pk_add_f32 v[214:215], v[90:91], v[226:227]
	v_pk_mul_f32 v[206:207], v[204:205], 0.5 op_sel_hi:[1,0]
	v_pk_mul_f32 v[216:217], v[214:215], 0.5 op_sel_hi:[1,0]
	v_pk_mul_f32 v[204:205], v[204:205], s[50:51] op_sel_hi:[1,0]
	v_pk_mul_f32 v[214:215], v[214:215], s[50:51] op_sel_hi:[1,0]
	v_mul_f32_e64 v208, |v204|, -|v204|
	v_mul_f32_e64 v218, |v214|, -|v214|
	v_mul_f32_e64 v209, |v205|, -|v205|
	v_mul_f32_e64 v219, |v215|, -|v215|
	v_fma_f32 v210, |v204|, s78, 1.0
	v_fma_f32 v128, |v214|, s78, 1.0
	v_fma_f32 v211, |v205|, s78, 1.0
	v_fma_f32 v129, |v215|, s78, 1.0
	v_mul_f32_e32 v208, 0x3fb8aa3b, v208
	v_mul_f32_e32 v218, 0x3fb8aa3b, v218
	v_mul_f32_e32 v209, 0x3fb8aa3b, v209
	v_mul_f32_e32 v219, 0x3fb8aa3b, v219
	v_rcp_f32_e32 v210, v210
	v_rcp_f32_e32 v128, v128
	v_rcp_f32_e32 v211, v211
	v_rcp_f32_e32 v129, v129
	v_exp_f32_e32 v208, v208
	v_exp_f32_e32 v218, v218
	v_exp_f32_e32 v209, v209
	v_exp_f32_e32 v219, v219
	v_pk_fma_f32 v[212:213], v[210:211], s[86:87], v[244:245] op_sel_hi:[1,0,1]
	v_pk_fma_f32 v[130:131], v[128:129], s[86:87], v[244:245] op_sel_hi:[1,0,1]
	v_pk_fma_f32 v[212:213], v[212:213], v[210:211], s[88:89] op_sel_hi:[1,1,0]
	v_pk_fma_f32 v[130:131], v[130:131], v[128:129], s[88:89] op_sel_hi:[1,1,0]
	v_pk_fma_f32 v[212:213], v[212:213], v[210:211], s[90:91] op_sel_hi:[1,1,0]
	v_pk_fma_f32 v[130:131], v[130:131], v[128:129], s[90:91] op_sel_hi:[1,1,0]
	v_pk_fma_f32 v[212:213], v[212:213], v[210:211], s[96:97] op_sel_hi:[1,1,0]
	v_pk_fma_f32 v[130:131], v[130:131], v[128:129], s[96:97] op_sel_hi:[1,1,0]
	v_pk_mul_f32 v[212:213], v[210:211], v[212:213]
	v_pk_mul_f32 v[130:131], v[128:129], v[130:131]
	v_pk_fma_f32 v[212:213], v[208:209], v[212:213], 1.0 op_sel_hi:[1,1,0] neg_lo:[1,0,0] neg_hi:[1,0,0]
	v_pk_fma_f32 v[130:131], v[218:219], v[130:131], 1.0 op_sel_hi:[1,1,0] neg_lo:[1,0,0] neg_hi:[1,0,0]
	v_bfi_b32 v204, s35, v212, v204
	v_bfi_b32 v214, s35, v130, v214
	v_bfi_b32 v205, s35, v213, v205
	v_bfi_b32 v215, s35, v131, v215
	v_pk_add_f32 v[204:205], v[204:205], 1.0 op_sel_hi:[1,0]
	v_pk_add_f32 v[214:215], v[214:215], 1.0 op_sel_hi:[1,0]
	v_pk_mul_f32 v[206:207], v[206:207], v[204:205]
	v_pk_mul_f32 v[216:217], v[216:217], v[214:215]
	v_cvt_pk_bf16_f32 v154, v206, v207
	v_cvt_pk_bf16_f32 v155, v216, v217
	ds_write_b64 v149, v[154:155]
	v_pk_add_f32 v[204:205], v[84:85], v[228:229]
	v_pk_add_f32 v[214:215], v[86:87], v[230:231]
	v_pk_mul_f32 v[206:207], v[204:205], 0.5 op_sel_hi:[1,0]
	v_pk_mul_f32 v[216:217], v[214:215], 0.5 op_sel_hi:[1,0]
	v_pk_mul_f32 v[204:205], v[204:205], s[50:51] op_sel_hi:[1,0]
	v_pk_mul_f32 v[214:215], v[214:215], s[50:51] op_sel_hi:[1,0]
	v_mul_f32_e64 v208, |v204|, -|v204|
	v_mul_f32_e64 v218, |v214|, -|v214|
	v_mul_f32_e64 v209, |v205|, -|v205|
	v_mul_f32_e64 v219, |v215|, -|v215|
	v_fma_f32 v210, |v204|, s78, 1.0
	v_fma_f32 v128, |v214|, s78, 1.0
	v_fma_f32 v211, |v205|, s78, 1.0
	v_fma_f32 v129, |v215|, s78, 1.0
	v_mul_f32_e32 v208, 0x3fb8aa3b, v208
	v_mul_f32_e32 v218, 0x3fb8aa3b, v218
	v_mul_f32_e32 v209, 0x3fb8aa3b, v209
	v_mul_f32_e32 v219, 0x3fb8aa3b, v219
	v_rcp_f32_e32 v210, v210
	v_rcp_f32_e32 v128, v128
	v_rcp_f32_e32 v211, v211
	v_rcp_f32_e32 v129, v129
	v_exp_f32_e32 v208, v208
	v_exp_f32_e32 v218, v218
	v_exp_f32_e32 v209, v209
	v_exp_f32_e32 v219, v219
	v_pk_fma_f32 v[212:213], v[210:211], s[86:87], v[244:245] op_sel_hi:[1,0,1]
	v_pk_fma_f32 v[130:131], v[128:129], s[86:87], v[244:245] op_sel_hi:[1,0,1]
	v_pk_fma_f32 v[212:213], v[212:213], v[210:211], s[88:89] op_sel_hi:[1,1,0]
	v_pk_fma_f32 v[130:131], v[130:131], v[128:129], s[88:89] op_sel_hi:[1,1,0]
	v_pk_fma_f32 v[212:213], v[212:213], v[210:211], s[90:91] op_sel_hi:[1,1,0]
	v_pk_fma_f32 v[130:131], v[130:131], v[128:129], s[90:91] op_sel_hi:[1,1,0]
	v_pk_fma_f32 v[212:213], v[212:213], v[210:211], s[96:97] op_sel_hi:[1,1,0]
	v_pk_fma_f32 v[130:131], v[130:131], v[128:129], s[96:97] op_sel_hi:[1,1,0]
	v_pk_mul_f32 v[212:213], v[210:211], v[212:213]
	v_pk_mul_f32 v[130:131], v[128:129], v[130:131]
	v_pk_fma_f32 v[212:213], v[208:209], v[212:213], 1.0 op_sel_hi:[1,1,0] neg_lo:[1,0,0] neg_hi:[1,0,0]
	v_pk_fma_f32 v[130:131], v[218:219], v[130:131], 1.0 op_sel_hi:[1,1,0] neg_lo:[1,0,0] neg_hi:[1,0,0]
	v_bfi_b32 v204, s35, v212, v204
	v_bfi_b32 v214, s35, v130, v214
	v_bfi_b32 v205, s35, v213, v205
	v_bfi_b32 v215, s35, v131, v215
	v_pk_add_f32 v[204:205], v[204:205], 1.0 op_sel_hi:[1,0]
	v_pk_add_f32 v[214:215], v[214:215], 1.0 op_sel_hi:[1,0]
	v_pk_mul_f32 v[206:207], v[206:207], v[204:205]
	v_pk_mul_f32 v[216:217], v[216:217], v[214:215]
	v_cvt_pk_bf16_f32 v152, v206, v207
	v_cvt_pk_bf16_f32 v153, v216, v217
	ds_write_b64 v150, v[152:153]
	v_pk_add_f32 v[204:205], v[80:81], v[232:233]
	v_pk_add_f32 v[214:215], v[82:83], v[234:235]
	v_pk_mul_f32 v[206:207], v[204:205], 0.5 op_sel_hi:[1,0]
	v_pk_mul_f32 v[216:217], v[214:215], 0.5 op_sel_hi:[1,0]
	v_pk_mul_f32 v[204:205], v[204:205], s[50:51] op_sel_hi:[1,0]
	v_pk_mul_f32 v[214:215], v[214:215], s[50:51] op_sel_hi:[1,0]
	v_mul_f32_e64 v208, |v204|, -|v204|
	v_mul_f32_e64 v218, |v214|, -|v214|
; __device__ __forceinline__ float erf_fast(float x) {
;   const float ax = fabsf(x);
;   const float t = __builtin_amdgcn_rcpf(fmaf(0.3275911f, ax, 1.0f));
;   float p = fmaf(1.061405429f, t, -1.453152027f);
;   p = fmaf(p, t, 1.421413741f); p = fmaf(p, t, -0.284496736f); p = fmaf(p, t, 0.254829592f);
;   const float e = 1.0f - p * t * __expf(-ax * ax);
;   return copysignf(e, x);
; }
; template <int MODE> __device__ __forceinline__ void epi_store(const GemmDesc& g, int row, int col, f32x4 v) {
;     ...
;     case E_GELU: {
;       const float4 bb = *(const float4*)(g.b0 + col);
;       float t[4] = {v[0] + bb.x, v[1] + bb.y, v[2] + bb.z, v[3] + bb.w};
; #pragma unroll
;       for (int i = 0; i < 4; ++i) t[i] = 0.5f * t[i] * (1.0f + erf_fast(t[i] * 0.70710678118654752f));
;       uint2 o; o.x = pack2(t[0], t[1]); o.y = pack2(t[2], t[3]);
;       *(uint2*)((u16*)g.o0 + (size_t)row * g.ldo + col) = o;
;     } break;
	v_mul_f32_e64 v209, |v205|, -|v205|
	v_mul_f32_e64 v219, |v215|, -|v215|
	v_fma_f32 v210, |v204|, s78, 1.0
	v_fma_f32 v128, |v214|, s78, 1.0
	v_fma_f32 v211, |v205|, s78, 1.0
	v_fma_f32 v129, |v215|, s78, 1.0
	v_mul_f32_e32 v208, 0x3fb8aa3b, v208
	v_mul_f32_e32 v218, 0x3fb8aa3b, v218
	v_mul_f32_e32 v209, 0x3fb8aa3b, v209
	v_mul_f32_e32 v219, 0x3fb8aa3b, v219
	v_rcp_f32_e32 v210, v210
	v_rcp_f32_e32 v128, v128
	v_rcp_f32_e32 v211, v211
	v_rcp_f32_e32 v129, v129
	v_exp_f32_e32 v208, v208
	v_exp_f32_e32 v218, v218
	v_exp_f32_e32 v209, v209
	v_exp_f32_e32 v219, v219
	v_pk_fma_f32 v[212:213], v[210:211], s[86:87], v[244:245] op_sel_hi:[1,0,1]
	v_pk_fma_f32 v[130:131], v[128:129], s[86:87], v[244:245] op_sel_hi:[1,0,1]
	v_pk_fma_f32 v[212:213], v[212:213], v[210:211], s[88:89] op_sel_hi:[1,1,0]
	v_pk_fma_f32 v[130:131], v[130:131], v[128:129], s[88:89] op_sel_hi:[1,1,0]
	v_pk_fma_f32 v[212:213], v[212:213], v[210:211], s[90:91] op_sel_hi:[1,1,0]
	v_pk_fma_f32 v[130:131], v[130:131], v[128:129], s[90:91] op_sel_hi:[1,1,0]
	v_pk_fma_f32 v[212:213], v[212:213], v[210:211], s[96:97] op_sel_hi:[1,1,0]
	v_pk_fma_f32 v[130:131], v[130:131], v[128:129], s[96:97] op_sel_hi:[1,1,0]
	v_pk_mul_f32 v[212:213], v[210:211], v[212:213]
	v_pk_mul_f32 v[130:131], v[128:129], v[130:131]
	v_pk_fma_f32 v[212:213], v[208:209], v[212:213], 1.0 op_sel_hi:[1,1,0] neg_lo:[1,0,0] neg_hi:[1,0,0]
	v_pk_fma_f32 v[130:131], v[218:219], v[130:131], 1.0 op_sel_hi:[1,1,0] neg_lo:[1,0,0] neg_hi:[1,0,0]
	v_bfi_b32 v204, s35, v212, v204
	v_bfi_b32 v214, s35, v130, v214
	v_bfi_b32 v205, s35, v213, v205
	v_bfi_b32 v215, s35, v131, v215
	v_pk_add_f32 v[204:205], v[204:205], 1.0 op_sel_hi:[1,0]
	v_pk_add_f32 v[214:215], v[214:215], 1.0 op_sel_hi:[1,0]
	v_pk_mul_f32 v[206:207], v[206:207], v[204:205]
	v_pk_mul_f32 v[216:217], v[216:217], v[214:215]
	v_cvt_pk_bf16_f32 v154, v206, v207
	v_cvt_pk_bf16_f32 v155, v216, v217
	ds_write_b64 v151, v[154:155]
	s_waitcnt lgkmcnt(4)
	global_store_dwordx4 v146, v[236:239], s[66:67]
	global_store_dwordx4 v147, v[240:243], s[66:67]
	v_add_u32_e32 v146, s5, v146
	v_add_u32_e32 v147, s5, v147
	ds_read_b128 v[236:239], v156
	ds_read_b128 v[240:243], v156 offset:1024
	v_pk_add_f32 v[204:205], v[76:77], v[220:221]
	v_pk_add_f32 v[214:215], v[78:79], v[222:223]
	v_pk_mul_f32 v[206:207], v[204:205], 0.5 op_sel_hi:[1,0]
	v_pk_mul_f32 v[216:217], v[214:215], 0.5 op_sel_hi:[1,0]
	v_pk_mul_f32 v[204:205], v[204:205], s[50:51] op_sel_hi:[1,0]
	v_pk_mul_f32 v[214:215], v[214:215], s[50:51] op_sel_hi:[1,0]
	v_mul_f32_e64 v208, |v204|, -|v204|
	v_mul_f32_e64 v218, |v214|, -|v214|
	v_mul_f32_e64 v209, |v205|, -|v205|
	v_mul_f32_e64 v219, |v215|, -|v215|
	v_fma_f32 v210, |v204|, s78, 1.0
	v_fma_f32 v128, |v214|, s78, 1.0
	v_fma_f32 v211, |v205|, s78, 1.0
	v_fma_f32 v129, |v215|, s78, 1.0
	v_mul_f32_e32 v208, 0x3fb8aa3b, v208
	v_mul_f32_e32 v218, 0x3fb8aa3b, v218
	v_mul_f32_e32 v209, 0x3fb8aa3b, v209
	v_mul_f32_e32 v219, 0x3fb8aa3b, v219
	v_rcp_f32_e32 v210, v210
	v_rcp_f32_e32 v128, v128
	v_rcp_f32_e32 v211, v211
	v_rcp_f32_e32 v129, v129
	v_exp_f32_e32 v208, v208
	v_exp_f32_e32 v218, v218
	v_exp_f32_e32 v209, v209
	v_exp_f32_e32 v219, v219
	v_pk_fma_f32 v[212:213], v[210:211], s[86:87], v[244:245] op_sel_hi:[1,0,1]
	v_pk_fma_f32 v[130:131], v[128:129], s[86:87], v[244:245] op_sel_hi:[1,0,1]
	v_pk_fma_f32 v[212:213], v[212:213], v[210:211], s[88:89] op_sel_hi:[1,1,0]
	v_pk_fma_f32 v[130:131], v[130:131], v[128:129], s[88:89] op_sel_hi:[1,1,0]
	v_pk_fma_f32 v[212:213], v[212:213], v[210:211], s[90:91] op_sel_hi:[1,1,0]
	v_pk_fma_f32 v[130:131], v[130:131], v[128:129], s[90:91] op_sel_hi:[1,1,0]
	v_pk_fma_f32 v[212:213], v[212:213], v[210:211], s[96:97] op_sel_hi:[1,1,0]
	v_pk_fma_f32 v[130:131], v[130:131], v[128:129], s[96:97] op_sel_hi:[1,1,0]
	v_pk_mul_f32 v[212:213], v[210:211], v[212:213]
	v_pk_mul_f32 v[130:131], v[128:129], v[130:131]
	v_pk_fma_f32 v[212:213], v[208:209], v[212:213], 1.0 op_sel_hi:[1,1,0] neg_lo:[1,0,0] neg_hi:[1,0,0]
	v_pk_fma_f32 v[130:131], v[218:219], v[130:131], 1.0 op_sel_hi:[1,1,0] neg_lo:[1,0,0] neg_hi:[1,0,0]
	v_bfi_b32 v204, s35, v212, v204
	v_bfi_b32 v214, s35, v130, v214
	v_bfi_b32 v205, s35, v213, v205
	v_bfi_b32 v215, s35, v131, v215
	v_pk_add_f32 v[204:205], v[204:205], 1.0 op_sel_hi:[1,0]
	v_pk_add_f32 v[214:215], v[214:215], 1.0 op_sel_hi:[1,0]
	v_pk_mul_f32 v[206:207], v[206:207], v[204:205]
	v_pk_mul_f32 v[216:217], v[216:217], v[214:215]
	v_cvt_pk_bf16_f32 v152, v206, v207
	v_cvt_pk_bf16_f32 v153, v216, v217
	ds_write_b64 v148, v[152:153]
	v_pk_add_f32 v[204:205], v[72:73], v[224:225]
	v_pk_add_f32 v[214:215], v[74:75], v[226:227]
	v_pk_mul_f32 v[206:207], v[204:205], 0.5 op_sel_hi:[1,0]
	v_pk_mul_f32 v[216:217], v[214:215], 0.5 op_sel_hi:[1,0]
	v_pk_mul_f32 v[204:205], v[204:205], s[50:51] op_sel_hi:[1,0]
	v_pk_mul_f32 v[214:215], v[214:215], s[50:51] op_sel_hi:[1,0]
	v_mul_f32_e64 v208, |v204|, -|v204|
	v_mul_f32_e64 v218, |v214|, -|v214|
	v_mul_f32_e64 v209, |v205|, -|v205|
	v_mul_f32_e64 v219, |v215|, -|v215|
	v_fma_f32 v210, |v204|, s78, 1.0
	v_fma_f32 v128, |v214|, s78, 1.0
	v_fma_f32 v211, |v205|, s78, 1.0
	v_fma_f32 v129, |v215|, s78, 1.0
	v_mul_f32_e32 v208, 0x3fb8aa3b, v208
	v_mul_f32_e32 v218, 0x3fb8aa3b, v218
	v_mul_f32_e32 v209, 0x3fb8aa3b, v209
	v_mul_f32_e32 v219, 0x3fb8aa3b, v219
	v_rcp_f32_e32 v210, v210
	v_rcp_f32_e32 v128, v128
	v_rcp_f32_e32 v211, v211
	v_rcp_f32_e32 v129, v129
	v_exp_f32_e32 v208, v208
	v_exp_f32_e32 v218, v218
	v_exp_f32_e32 v209, v209
	v_exp_f32_e32 v219, v219
	v_pk_fma_f32 v[212:213], v[210:211], s[86:87], v[244:245] op_sel_hi:[1,0,1]
	v_pk_fma_f32 v[130:131], v[128:129], s[86:87], v[244:245] op_sel_hi:[1,0,1]
; __device__ __forceinline__ float erf_fast(float x) {
;   const float ax = fabsf(x);
;   const float t = __builtin_amdgcn_rcpf(fmaf(0.3275911f, ax, 1.0f));
;   float p = fmaf(1.061405429f, t, -1.453152027f);
;   p = fmaf(p, t, 1.421413741f); p = fmaf(p, t, -0.284496736f); p = fmaf(p, t, 0.254829592f);
;   const float e = 1.0f - p * t * __expf(-ax * ax);
;   return copysignf(e, x);
; }
; template <int MODE> __device__ __forceinline__ void epi_store(const GemmDesc& g, int row, int col, f32x4 v) {
;     ...
;     case E_GELU: {
;       const float4 bb = *(const float4*)(g.b0 + col);
;       float t[4] = {v[0] + bb.x, v[1] + bb.y, v[2] + bb.z, v[3] + bb.w};
; #pragma unroll
;       for (int i = 0; i < 4; ++i) t[i] = 0.5f * t[i] * (1.0f + erf_fast(t[i] * 0.70710678118654752f));
;       uint2 o; o.x = pack2(t[0], t[1]); o.y = pack2(t[2], t[3]);
;       *(uint2*)((u16*)g.o0 + (size_t)row * g.ldo + col) = o;
;     } break;
	v_pk_fma_f32 v[212:213], v[212:213], v[210:211], s[88:89] op_sel_hi:[1,1,0]
	v_pk_fma_f32 v[130:131], v[130:131], v[128:129], s[88:89] op_sel_hi:[1,1,0]
	v_pk_fma_f32 v[212:213], v[212:213], v[210:211], s[90:91] op_sel_hi:[1,1,0]
	v_pk_fma_f32 v[130:131], v[130:131], v[128:129], s[90:91] op_sel_hi:[1,1,0]
	v_pk_fma_f32 v[212:213], v[212:213], v[210:211], s[96:97] op_sel_hi:[1,1,0]
	v_pk_fma_f32 v[130:131], v[130:131], v[128:129], s[96:97] op_sel_hi:[1,1,0]
	v_pk_mul_f32 v[212:213], v[210:211], v[212:213]
	v_pk_mul_f32 v[130:131], v[128:129], v[130:131]
	v_pk_fma_f32 v[212:213], v[208:209], v[212:213], 1.0 op_sel_hi:[1,1,0] neg_lo:[1,0,0] neg_hi:[1,0,0]
	v_pk_fma_f32 v[130:131], v[218:219], v[130:131], 1.0 op_sel_hi:[1,1,0] neg_lo:[1,0,0] neg_hi:[1,0,0]
	v_bfi_b32 v204, s35, v212, v204
	v_bfi_b32 v214, s35, v130, v214
	v_bfi_b32 v205, s35, v213, v205
	v_bfi_b32 v215, s35, v131, v215
	v_pk_add_f32 v[204:205], v[204:205], 1.0 op_sel_hi:[1,0]
	v_pk_add_f32 v[214:215], v[214:215], 1.0 op_sel_hi:[1,0]
	v_pk_mul_f32 v[206:207], v[206:207], v[204:205]
	v_pk_mul_f32 v[216:217], v[216:217], v[214:215]
	v_cvt_pk_bf16_f32 v154, v206, v207
	v_cvt_pk_bf16_f32 v155, v216, v217
	ds_write_b64 v149, v[154:155]
	v_pk_add_f32 v[204:205], v[68:69], v[228:229]
	v_pk_add_f32 v[214:215], v[70:71], v[230:231]
	v_pk_mul_f32 v[206:207], v[204:205], 0.5 op_sel_hi:[1,0]
	v_pk_mul_f32 v[216:217], v[214:215], 0.5 op_sel_hi:[1,0]
	v_pk_mul_f32 v[204:205], v[204:205], s[50:51] op_sel_hi:[1,0]
	v_pk_mul_f32 v[214:215], v[214:215], s[50:51] op_sel_hi:[1,0]
	v_mul_f32_e64 v208, |v204|, -|v204|
	v_mul_f32_e64 v218, |v214|, -|v214|
	v_mul_f32_e64 v209, |v205|, -|v205|
	v_mul_f32_e64 v219, |v215|, -|v215|
	v_fma_f32 v210, |v204|, s78, 1.0
	v_fma_f32 v128, |v214|, s78, 1.0
	v_fma_f32 v211, |v205|, s78, 1.0
	v_fma_f32 v129, |v215|, s78, 1.0
	v_mul_f32_e32 v208, 0x3fb8aa3b, v208
	v_mul_f32_e32 v218, 0x3fb8aa3b, v218
	v_mul_f32_e32 v209, 0x3fb8aa3b, v209
	v_mul_f32_e32 v219, 0x3fb8aa3b, v219
	v_rcp_f32_e32 v210, v210
	v_rcp_f32_e32 v128, v128
	v_rcp_f32_e32 v211, v211
	v_rcp_f32_e32 v129, v129
	v_exp_f32_e32 v208, v208
	v_exp_f32_e32 v218, v218
	v_exp_f32_e32 v209, v209
	v_exp_f32_e32 v219, v219
	v_pk_fma_f32 v[212:213], v[210:211], s[86:87], v[244:245] op_sel_hi:[1,0,1]
	v_pk_fma_f32 v[130:131], v[128:129], s[86:87], v[244:245] op_sel_hi:[1,0,1]
	v_pk_fma_f32 v[212:213], v[212:213], v[210:211], s[88:89] op_sel_hi:[1,1,0]
	v_pk_fma_f32 v[130:131], v[130:131], v[128:129], s[88:89] op_sel_hi:[1,1,0]
	v_pk_fma_f32 v[212:213], v[212:213], v[210:211], s[90:91] op_sel_hi:[1,1,0]
	v_pk_fma_f32 v[130:131], v[130:131], v[128:129], s[90:91] op_sel_hi:[1,1,0]
	v_pk_fma_f32 v[212:213], v[212:213], v[210:211], s[96:97] op_sel_hi:[1,1,0]
	v_pk_fma_f32 v[130:131], v[130:131], v[128:129], s[96:97] op_sel_hi:[1,1,0]
	v_pk_mul_f32 v[212:213], v[210:211], v[212:213]
	v_pk_mul_f32 v[130:131], v[128:129], v[130:131]
	v_pk_fma_f32 v[212:213], v[208:209], v[212:213], 1.0 op_sel_hi:[1,1,0] neg_lo:[1,0,0] neg_hi:[1,0,0]
	v_pk_fma_f32 v[130:131], v[218:219], v[130:131], 1.0 op_sel_hi:[1,1,0] neg_lo:[1,0,0] neg_hi:[1,0,0]
	v_bfi_b32 v204, s35, v212, v204
	v_bfi_b32 v214, s35, v130, v214
	v_bfi_b32 v205, s35, v213, v205
	v_bfi_b32 v215, s35, v131, v215
	v_pk_add_f32 v[204:205], v[204:205], 1.0 op_sel_hi:[1,0]
	v_pk_add_f32 v[214:215], v[214:215], 1.0 op_sel_hi:[1,0]
	v_pk_mul_f32 v[206:207], v[206:207], v[204:205]
	v_pk_mul_f32 v[216:217], v[216:217], v[214:215]
	v_cvt_pk_bf16_f32 v152, v206, v207
	v_cvt_pk_bf16_f32 v153, v216, v217
	ds_write_b64 v150, v[152:153]
	v_pk_add_f32 v[204:205], v[64:65], v[232:233]
	v_pk_add_f32 v[214:215], v[66:67], v[234:235]
	v_pk_mul_f32 v[206:207], v[204:205], 0.5 op_sel_hi:[1,0]
	v_pk_mul_f32 v[216:217], v[214:215], 0.5 op_sel_hi:[1,0]
	v_pk_mul_f32 v[204:205], v[204:205], s[50:51] op_sel_hi:[1,0]
	v_pk_mul_f32 v[214:215], v[214:215], s[50:51] op_sel_hi:[1,0]
	v_mul_f32_e64 v208, |v204|, -|v204|
	v_mul_f32_e64 v218, |v214|, -|v214|
	v_mul_f32_e64 v209, |v205|, -|v205|
	v_mul_f32_e64 v219, |v215|, -|v215|
	v_fma_f32 v210, |v204|, s78, 1.0
	v_fma_f32 v128, |v214|, s78, 1.0
	v_fma_f32 v211, |v205|, s78, 1.0
	v_fma_f32 v129, |v215|, s78, 1.0
	v_mul_f32_e32 v208, 0x3fb8aa3b, v208
	v_mul_f32_e32 v218, 0x3fb8aa3b, v218
	v_mul_f32_e32 v209, 0x3fb8aa3b, v209
	v_mul_f32_e32 v219, 0x3fb8aa3b, v219
	v_rcp_f32_e32 v210, v210
	v_rcp_f32_e32 v128, v128
	v_rcp_f32_e32 v211, v211
	v_rcp_f32_e32 v129, v129
	v_exp_f32_e32 v208, v208
	v_exp_f32_e32 v218, v218
	v_exp_f32_e32 v209, v209
	v_exp_f32_e32 v219, v219
	v_pk_fma_f32 v[212:213], v[210:211], s[86:87], v[244:245] op_sel_hi:[1,0,1]
	v_pk_fma_f32 v[130:131], v[128:129], s[86:87], v[244:245] op_sel_hi:[1,0,1]
	v_pk_fma_f32 v[212:213], v[212:213], v[210:211], s[88:89] op_sel_hi:[1,1,0]
	v_pk_fma_f32 v[130:131], v[130:131], v[128:129], s[88:89] op_sel_hi:[1,1,0]
	v_pk_fma_f32 v[212:213], v[212:213], v[210:211], s[90:91] op_sel_hi:[1,1,0]
	v_pk_fma_f32 v[130:131], v[130:131], v[128:129], s[90:91] op_sel_hi:[1,1,0]
	v_pk_fma_f32 v[212:213], v[212:213], v[210:211], s[96:97] op_sel_hi:[1,1,0]
	v_pk_fma_f32 v[130:131], v[130:131], v[128:129], s[96:97] op_sel_hi:[1,1,0]
	v_pk_mul_f32 v[212:213], v[210:211], v[212:213]
	v_pk_mul_f32 v[130:131], v[128:129], v[130:131]
	v_pk_fma_f32 v[212:213], v[208:209], v[212:213], 1.0 op_sel_hi:[1,1,0] neg_lo:[1,0,0] neg_hi:[1,0,0]
	v_pk_fma_f32 v[130:131], v[218:219], v[130:131], 1.0 op_sel_hi:[1,1,0] neg_lo:[1,0,0] neg_hi:[1,0,0]
	v_bfi_b32 v204, s35, v212, v204
	v_bfi_b32 v214, s35, v130, v214
	v_bfi_b32 v205, s35, v213, v205
	v_bfi_b32 v215, s35, v131, v215
	v_pk_add_f32 v[204:205], v[204:205], 1.0 op_sel_hi:[1,0]
	v_pk_add_f32 v[214:215], v[214:215], 1.0 op_sel_hi:[1,0]
	v_pk_mul_f32 v[206:207], v[206:207], v[204:205]
	v_pk_mul_f32 v[216:217], v[216:217], v[214:215]
	v_cvt_pk_bf16_f32 v154, v206, v207
	v_cvt_pk_bf16_f32 v155, v216, v217
	ds_write_b64 v151, v[154:155]
	s_waitcnt lgkmcnt(4)
; __device__ __forceinline__ float erf_fast(float x) {
;   const float ax = fabsf(x);
;   const float t = __builtin_amdgcn_rcpf(fmaf(0.3275911f, ax, 1.0f));
;   float p = fmaf(1.061405429f, t, -1.453152027f);
;   p = fmaf(p, t, 1.421413741f); p = fmaf(p, t, -0.284496736f); p = fmaf(p, t, 0.254829592f);
;   const float e = 1.0f - p * t * __expf(-ax * ax);
;   return copysignf(e, x);
; }
; template <int MODE> __device__ __forceinline__ void epi_store(const GemmDesc& g, int row, int col, f32x4 v) {
;     ...
;     case E_GELU: {
;       const float4 bb = *(const float4*)(g.b0 + col);
;       float t[4] = {v[0] + bb.x, v[1] + bb.y, v[2] + bb.z, v[3] + bb.w};
; #pragma unroll
;       for (int i = 0; i < 4; ++i) t[i] = 0.5f * t[i] * (1.0f + erf_fast(t[i] * 0.70710678118654752f));
;       uint2 o; o.x = pack2(t[0], t[1]); o.y = pack2(t[2], t[3]);
;       *(uint2*)((u16*)g.o0 + (size_t)row * g.ldo + col) = o;
;     } break;
	global_store_dwordx4 v146, v[236:239], s[66:67]
	global_store_dwordx4 v147, v[240:243], s[66:67]
	v_add_u32_e32 v146, s5, v146
	v_add_u32_e32 v147, s5, v147
	ds_read_b128 v[236:239], v156
	ds_read_b128 v[240:243], v156 offset:1024
	v_pk_add_f32 v[204:205], v[60:61], v[220:221]
	v_pk_add_f32 v[214:215], v[62:63], v[222:223]
	v_pk_mul_f32 v[206:207], v[204:205], 0.5 op_sel_hi:[1,0]
	v_pk_mul_f32 v[216:217], v[214:215], 0.5 op_sel_hi:[1,0]
	v_pk_mul_f32 v[204:205], v[204:205], s[50:51] op_sel_hi:[1,0]
	v_pk_mul_f32 v[214:215], v[214:215], s[50:51] op_sel_hi:[1,0]
	v_mul_f32_e64 v208, |v204|, -|v204|
	v_mul_f32_e64 v218, |v214|, -|v214|
	v_mul_f32_e64 v209, |v205|, -|v205|
	v_mul_f32_e64 v219, |v215|, -|v215|
	v_fma_f32 v210, |v204|, s78, 1.0
	v_fma_f32 v128, |v214|, s78, 1.0
	v_fma_f32 v211, |v205|, s78, 1.0
	v_fma_f32 v129, |v215|, s78, 1.0
	v_mul_f32_e32 v208, 0x3fb8aa3b, v208
	v_mul_f32_e32 v218, 0x3fb8aa3b, v218
	v_mul_f32_e32 v209, 0x3fb8aa3b, v209
	v_mul_f32_e32 v219, 0x3fb8aa3b, v219
	v_rcp_f32_e32 v210, v210
	v_rcp_f32_e32 v128, v128
	v_rcp_f32_e32 v211, v211
	v_rcp_f32_e32 v129, v129
	v_exp_f32_e32 v208, v208
	v_exp_f32_e32 v218, v218
	v_exp_f32_e32 v209, v209
	v_exp_f32_e32 v219, v219
	v_pk_fma_f32 v[212:213], v[210:211], s[86:87], v[244:245] op_sel_hi:[1,0,1]
	v_pk_fma_f32 v[130:131], v[128:129], s[86:87], v[244:245] op_sel_hi:[1,0,1]
	v_pk_fma_f32 v[212:213], v[212:213], v[210:211], s[88:89] op_sel_hi:[1,1,0]
	v_pk_fma_f32 v[130:131], v[130:131], v[128:129], s[88:89] op_sel_hi:[1,1,0]
	v_pk_fma_f32 v[212:213], v[212:213], v[210:211], s[90:91] op_sel_hi:[1,1,0]
	v_pk_fma_f32 v[130:131], v[130:131], v[128:129], s[90:91] op_sel_hi:[1,1,0]
	v_pk_fma_f32 v[212:213], v[212:213], v[210:211], s[96:97] op_sel_hi:[1,1,0]
	v_pk_fma_f32 v[130:131], v[130:131], v[128:129], s[96:97] op_sel_hi:[1,1,0]
	v_pk_mul_f32 v[212:213], v[210:211], v[212:213]
	v_pk_mul_f32 v[130:131], v[128:129], v[130:131]
	v_pk_fma_f32 v[212:213], v[208:209], v[212:213], 1.0 op_sel_hi:[1,1,0] neg_lo:[1,0,0] neg_hi:[1,0,0]
	v_pk_fma_f32 v[130:131], v[218:219], v[130:131], 1.0 op_sel_hi:[1,1,0] neg_lo:[1,0,0] neg_hi:[1,0,0]
	v_bfi_b32 v204, s35, v212, v204
	v_bfi_b32 v214, s35, v130, v214
	v_bfi_b32 v205, s35, v213, v205
	v_bfi_b32 v215, s35, v131, v215
	v_pk_add_f32 v[204:205], v[204:205], 1.0 op_sel_hi:[1,0]
	v_pk_add_f32 v[214:215], v[214:215], 1.0 op_sel_hi:[1,0]
	v_pk_mul_f32 v[206:207], v[206:207], v[204:205]
	v_pk_mul_f32 v[216:217], v[216:217], v[214:215]
	v_cvt_pk_bf16_f32 v152, v206, v207
	v_cvt_pk_bf16_f32 v153, v216, v217
	ds_write_b64 v148, v[152:153]
	v_pk_add_f32 v[204:205], v[56:57], v[224:225]
	v_pk_add_f32 v[214:215], v[58:59], v[226:227]
	v_pk_mul_f32 v[206:207], v[204:205], 0.5 op_sel_hi:[1,0]
	v_pk_mul_f32 v[216:217], v[214:215], 0.5 op_sel_hi:[1,0]
	v_pk_mul_f32 v[204:205], v[204:205], s[50:51] op_sel_hi:[1,0]
	v_pk_mul_f32 v[214:215], v[214:215], s[50:51] op_sel_hi:[1,0]
	v_mul_f32_e64 v208, |v204|, -|v204|
	v_mul_f32_e64 v218, |v214|, -|v214|
	v_mul_f32_e64 v209, |v205|, -|v205|
	v_mul_f32_e64 v219, |v215|, -|v215|
	v_fma_f32 v210, |v204|, s78, 1.0
	v_fma_f32 v128, |v214|, s78, 1.0
	v_fma_f32 v211, |v205|, s78, 1.0
	v_fma_f32 v129, |v215|, s78, 1.0
	v_mul_f32_e32 v208, 0x3fb8aa3b, v208
	v_mul_f32_e32 v218, 0x3fb8aa3b, v218
	v_mul_f32_e32 v209, 0x3fb8aa3b, v209
	v_mul_f32_e32 v219, 0x3fb8aa3b, v219
	v_rcp_f32_e32 v210, v210
	v_rcp_f32_e32 v128, v128
	v_rcp_f32_e32 v211, v211
	v_rcp_f32_e32 v129, v129
	v_exp_f32_e32 v208, v208
	v_exp_f32_e32 v218, v218
	v_exp_f32_e32 v209, v209
	v_exp_f32_e32 v219, v219
	v_pk_fma_f32 v[212:213], v[210:211], s[86:87], v[244:245] op_sel_hi:[1,0,1]
	v_pk_fma_f32 v[130:131], v[128:129], s[86:87], v[244:245] op_sel_hi:[1,0,1]
	v_pk_fma_f32 v[212:213], v[212:213], v[210:211], s[88:89] op_sel_hi:[1,1,0]
	v_pk_fma_f32 v[130:131], v[130:131], v[128:129], s[88:89] op_sel_hi:[1,1,0]
	v_pk_fma_f32 v[212:213], v[212:213], v[210:211], s[90:91] op_sel_hi:[1,1,0]
	v_pk_fma_f32 v[130:131], v[130:131], v[128:129], s[90:91] op_sel_hi:[1,1,0]
	v_pk_fma_f32 v[212:213], v[212:213], v[210:211], s[96:97] op_sel_hi:[1,1,0]
	v_pk_fma_f32 v[130:131], v[130:131], v[128:129], s[96:97] op_sel_hi:[1,1,0]
	v_pk_mul_f32 v[212:213], v[210:211], v[212:213]
	v_pk_mul_f32 v[130:131], v[128:129], v[130:131]
	v_pk_fma_f32 v[212:213], v[208:209], v[212:213], 1.0 op_sel_hi:[1,1,0] neg_lo:[1,0,0] neg_hi:[1,0,0]
	v_pk_fma_f32 v[130:131], v[218:219], v[130:131], 1.0 op_sel_hi:[1,1,0] neg_lo:[1,0,0] neg_hi:[1,0,0]
	v_bfi_b32 v204, s35, v212, v204
	v_bfi_b32 v214, s35, v130, v214
	v_bfi_b32 v205, s35, v213, v205
	v_bfi_b32 v215, s35, v131, v215
	v_pk_add_f32 v[204:205], v[204:205], 1.0 op_sel_hi:[1,0]
	v_pk_add_f32 v[214:215], v[214:215], 1.0 op_sel_hi:[1,0]
	v_pk_mul_f32 v[206:207], v[206:207], v[204:205]
	v_pk_mul_f32 v[216:217], v[216:217], v[214:215]
	v_cvt_pk_bf16_f32 v154, v206, v207
	v_cvt_pk_bf16_f32 v155, v216, v217
	ds_write_b64 v149, v[154:155]
	v_pk_add_f32 v[204:205], v[52:53], v[228:229]
	v_pk_add_f32 v[214:215], v[54:55], v[230:231]
	v_pk_mul_f32 v[206:207], v[204:205], 0.5 op_sel_hi:[1,0]
	v_pk_mul_f32 v[216:217], v[214:215], 0.5 op_sel_hi:[1,0]
	v_pk_mul_f32 v[204:205], v[204:205], s[50:51] op_sel_hi:[1,0]
	v_pk_mul_f32 v[214:215], v[214:215], s[50:51] op_sel_hi:[1,0]
	v_mul_f32_e64 v208, |v204|, -|v204|
	v_mul_f32_e64 v218, |v214|, -|v214|
	v_mul_f32_e64 v209, |v205|, -|v205|
	v_mul_f32_e64 v219, |v215|, -|v215|
	v_fma_f32 v210, |v204|, s78, 1.0
	v_fma_f32 v128, |v214|, s78, 1.0
	v_fma_f32 v211, |v205|, s78, 1.0
	v_fma_f32 v129, |v215|, s78, 1.0
	v_mul_f32_e32 v208, 0x3fb8aa3b, v208
	v_mul_f32_e32 v218, 0x3fb8aa3b, v218
; __device__ __forceinline__ float erf_fast(float x) {
;   const float ax = fabsf(x);
;   const float t = __builtin_amdgcn_rcpf(fmaf(0.3275911f, ax, 1.0f));
;   float p = fmaf(1.061405429f, t, -1.453152027f);
;   p = fmaf(p, t, 1.421413741f); p = fmaf(p, t, -0.284496736f); p = fmaf(p, t, 0.254829592f);
;   const float e = 1.0f - p * t * __expf(-ax * ax);
;   return copysignf(e, x);
; }
; template <int MODE> __device__ __forceinline__ void epi_store(const GemmDesc& g, int row, int col, f32x4 v) {
;     ...
;     case E_GELU: {
;       const float4 bb = *(const float4*)(g.b0 + col);
;       float t[4] = {v[0] + bb.x, v[1] + bb.y, v[2] + bb.z, v[3] + bb.w};
; #pragma unroll
;       for (int i = 0; i < 4; ++i) t[i] = 0.5f * t[i] * (1.0f + erf_fast(t[i] * 0.70710678118654752f));
;       uint2 o; o.x = pack2(t[0], t[1]); o.y = pack2(t[2], t[3]);
;       *(uint2*)((u16*)g.o0 + (size_t)row * g.ldo + col) = o;
;     } break;
	v_mul_f32_e32 v209, 0x3fb8aa3b, v209
	v_mul_f32_e32 v219, 0x3fb8aa3b, v219
	v_rcp_f32_e32 v210, v210
	v_rcp_f32_e32 v128, v128
	v_rcp_f32_e32 v211, v211
	v_rcp_f32_e32 v129, v129
	v_exp_f32_e32 v208, v208
	v_exp_f32_e32 v218, v218
	v_exp_f32_e32 v209, v209
	v_exp_f32_e32 v219, v219
	v_pk_fma_f32 v[212:213], v[210:211], s[86:87], v[244:245] op_sel_hi:[1,0,1]
	v_pk_fma_f32 v[130:131], v[128:129], s[86:87], v[244:245] op_sel_hi:[1,0,1]
	v_pk_fma_f32 v[212:213], v[212:213], v[210:211], s[88:89] op_sel_hi:[1,1,0]
	v_pk_fma_f32 v[130:131], v[130:131], v[128:129], s[88:89] op_sel_hi:[1,1,0]
	v_pk_fma_f32 v[212:213], v[212:213], v[210:211], s[90:91] op_sel_hi:[1,1,0]
	v_pk_fma_f32 v[130:131], v[130:131], v[128:129], s[90:91] op_sel_hi:[1,1,0]
	v_pk_fma_f32 v[212:213], v[212:213], v[210:211], s[96:97] op_sel_hi:[1,1,0]
	v_pk_fma_f32 v[130:131], v[130:131], v[128:129], s[96:97] op_sel_hi:[1,1,0]
	v_pk_mul_f32 v[212:213], v[210:211], v[212:213]
	v_pk_mul_f32 v[130:131], v[128:129], v[130:131]
	v_pk_fma_f32 v[212:213], v[208:209], v[212:213], 1.0 op_sel_hi:[1,1,0] neg_lo:[1,0,0] neg_hi:[1,0,0]
	v_pk_fma_f32 v[130:131], v[218:219], v[130:131], 1.0 op_sel_hi:[1,1,0] neg_lo:[1,0,0] neg_hi:[1,0,0]
	v_bfi_b32 v204, s35, v212, v204
	v_bfi_b32 v214, s35, v130, v214
	v_bfi_b32 v205, s35, v213, v205
	v_bfi_b32 v215, s35, v131, v215
	v_pk_add_f32 v[204:205], v[204:205], 1.0 op_sel_hi:[1,0]
	v_pk_add_f32 v[214:215], v[214:215], 1.0 op_sel_hi:[1,0]
	v_pk_mul_f32 v[206:207], v[206:207], v[204:205]
	v_pk_mul_f32 v[216:217], v[216:217], v[214:215]
	v_cvt_pk_bf16_f32 v152, v206, v207
	v_cvt_pk_bf16_f32 v153, v216, v217
	ds_write_b64 v150, v[152:153]
	v_pk_add_f32 v[204:205], v[48:49], v[232:233]
	v_pk_add_f32 v[214:215], v[50:51], v[234:235]
	v_pk_mul_f32 v[206:207], v[204:205], 0.5 op_sel_hi:[1,0]
	v_pk_mul_f32 v[216:217], v[214:215], 0.5 op_sel_hi:[1,0]
	v_pk_mul_f32 v[204:205], v[204:205], s[50:51] op_sel_hi:[1,0]
	v_pk_mul_f32 v[214:215], v[214:215], s[50:51] op_sel_hi:[1,0]
	v_mul_f32_e64 v208, |v204|, -|v204|
	v_mul_f32_e64 v218, |v214|, -|v214|
	v_mul_f32_e64 v209, |v205|, -|v205|
	v_mul_f32_e64 v219, |v215|, -|v215|
	v_fma_f32 v210, |v204|, s78, 1.0
	v_fma_f32 v128, |v214|, s78, 1.0
	v_fma_f32 v211, |v205|, s78, 1.0
	v_fma_f32 v129, |v215|, s78, 1.0
	v_mul_f32_e32 v208, 0x3fb8aa3b, v208
	v_mul_f32_e32 v218, 0x3fb8aa3b, v218
	v_mul_f32_e32 v209, 0x3fb8aa3b, v209
	v_mul_f32_e32 v219, 0x3fb8aa3b, v219
	v_rcp_f32_e32 v210, v210
	v_rcp_f32_e32 v128, v128
	v_rcp_f32_e32 v211, v211
	v_rcp_f32_e32 v129, v129
	v_exp_f32_e32 v208, v208
	v_exp_f32_e32 v218, v218
	v_exp_f32_e32 v209, v209
	v_exp_f32_e32 v219, v219
	v_pk_fma_f32 v[212:213], v[210:211], s[86:87], v[244:245] op_sel_hi:[1,0,1]
	v_pk_fma_f32 v[130:131], v[128:129], s[86:87], v[244:245] op_sel_hi:[1,0,1]
	v_pk_fma_f32 v[212:213], v[212:213], v[210:211], s[88:89] op_sel_hi:[1,1,0]
	v_pk_fma_f32 v[130:131], v[130:131], v[128:129], s[88:89] op_sel_hi:[1,1,0]
	v_pk_fma_f32 v[212:213], v[212:213], v[210:211], s[90:91] op_sel_hi:[1,1,0]
	v_pk_fma_f32 v[130:131], v[130:131], v[128:129], s[90:91] op_sel_hi:[1,1,0]
	v_pk_fma_f32 v[212:213], v[212:213], v[210:211], s[96:97] op_sel_hi:[1,1,0]
	v_pk_fma_f32 v[130:131], v[130:131], v[128:129], s[96:97] op_sel_hi:[1,1,0]
	v_pk_mul_f32 v[212:213], v[210:211], v[212:213]
	v_pk_mul_f32 v[130:131], v[128:129], v[130:131]
	v_pk_fma_f32 v[212:213], v[208:209], v[212:213], 1.0 op_sel_hi:[1,1,0] neg_lo:[1,0,0] neg_hi:[1,0,0]
	v_pk_fma_f32 v[130:131], v[218:219], v[130:131], 1.0 op_sel_hi:[1,1,0] neg_lo:[1,0,0] neg_hi:[1,0,0]
	v_bfi_b32 v204, s35, v212, v204
	v_bfi_b32 v214, s35, v130, v214
	v_bfi_b32 v205, s35, v213, v205
	v_bfi_b32 v215, s35, v131, v215
	v_pk_add_f32 v[204:205], v[204:205], 1.0 op_sel_hi:[1,0]
	v_pk_add_f32 v[214:215], v[214:215], 1.0 op_sel_hi:[1,0]
	v_pk_mul_f32 v[206:207], v[206:207], v[204:205]
	v_pk_mul_f32 v[216:217], v[216:217], v[214:215]
	v_cvt_pk_bf16_f32 v154, v206, v207
	v_cvt_pk_bf16_f32 v155, v216, v217
	ds_write_b64 v151, v[154:155]
	s_waitcnt lgkmcnt(4)
	global_store_dwordx4 v146, v[236:239], s[66:67]
	global_store_dwordx4 v147, v[240:243], s[66:67]
	v_add_u32_e32 v146, s5, v146
	v_add_u32_e32 v147, s5, v147
	ds_read_b128 v[236:239], v156
	ds_read_b128 v[240:243], v156 offset:1024
	v_pk_add_f32 v[204:205], v[44:45], v[220:221]
	v_pk_add_f32 v[214:215], v[46:47], v[222:223]
	v_pk_mul_f32 v[206:207], v[204:205], 0.5 op_sel_hi:[1,0]
	v_pk_mul_f32 v[216:217], v[214:215], 0.5 op_sel_hi:[1,0]
	v_pk_mul_f32 v[204:205], v[204:205], s[50:51] op_sel_hi:[1,0]
	v_pk_mul_f32 v[214:215], v[214:215], s[50:51] op_sel_hi:[1,0]
	v_mul_f32_e64 v208, |v204|, -|v204|
	v_mul_f32_e64 v218, |v214|, -|v214|
	v_mul_f32_e64 v209, |v205|, -|v205|
	v_mul_f32_e64 v219, |v215|, -|v215|
	v_fma_f32 v210, |v204|, s78, 1.0
	v_fma_f32 v128, |v214|, s78, 1.0
	v_fma_f32 v211, |v205|, s78, 1.0
	v_fma_f32 v129, |v215|, s78, 1.0
	v_mul_f32_e32 v208, 0x3fb8aa3b, v208
	v_mul_f32_e32 v218, 0x3fb8aa3b, v218
	v_mul_f32_e32 v209, 0x3fb8aa3b, v209
	v_mul_f32_e32 v219, 0x3fb8aa3b, v219
	v_rcp_f32_e32 v210, v210
	v_rcp_f32_e32 v128, v128
	v_rcp_f32_e32 v211, v211
	v_rcp_f32_e32 v129, v129
	v_exp_f32_e32 v208, v208
	v_exp_f32_e32 v218, v218
	v_exp_f32_e32 v209, v209
	v_exp_f32_e32 v219, v219
	v_pk_fma_f32 v[212:213], v[210:211], s[86:87], v[244:245] op_sel_hi:[1,0,1]
	v_pk_fma_f32 v[130:131], v[128:129], s[86:87], v[244:245] op_sel_hi:[1,0,1]
	v_pk_fma_f32 v[212:213], v[212:213], v[210:211], s[88:89] op_sel_hi:[1,1,0]
	v_pk_fma_f32 v[130:131], v[130:131], v[128:129], s[88:89] op_sel_hi:[1,1,0]
	v_pk_fma_f32 v[212:213], v[212:213], v[210:211], s[90:91] op_sel_hi:[1,1,0]
; __device__ __forceinline__ float erf_fast(float x) {
;   const float ax = fabsf(x);
;   const float t = __builtin_amdgcn_rcpf(fmaf(0.3275911f, ax, 1.0f));
;   float p = fmaf(1.061405429f, t, -1.453152027f);
;   p = fmaf(p, t, 1.421413741f); p = fmaf(p, t, -0.284496736f); p = fmaf(p, t, 0.254829592f);
;   const float e = 1.0f - p * t * __expf(-ax * ax);
;   return copysignf(e, x);
; }
; template <int MODE> __device__ __forceinline__ void epi_store(const GemmDesc& g, int row, int col, f32x4 v) {
;     ...
;     case E_GELU: {
;       const float4 bb = *(const float4*)(g.b0 + col);
;       float t[4] = {v[0] + bb.x, v[1] + bb.y, v[2] + bb.z, v[3] + bb.w};
; #pragma unroll
;       for (int i = 0; i < 4; ++i) t[i] = 0.5f * t[i] * (1.0f + erf_fast(t[i] * 0.70710678118654752f));
;       uint2 o; o.x = pack2(t[0], t[1]); o.y = pack2(t[2], t[3]);
;       *(uint2*)((u16*)g.o0 + (size_t)row * g.ldo + col) = o;
;     } break;
	v_pk_fma_f32 v[130:131], v[130:131], v[128:129], s[90:91] op_sel_hi:[1,1,0]
	v_pk_fma_f32 v[212:213], v[212:213], v[210:211], s[96:97] op_sel_hi:[1,1,0]
	v_pk_fma_f32 v[130:131], v[130:131], v[128:129], s[96:97] op_sel_hi:[1,1,0]
	v_pk_mul_f32 v[212:213], v[210:211], v[212:213]
	v_pk_mul_f32 v[130:131], v[128:129], v[130:131]
	v_pk_fma_f32 v[212:213], v[208:209], v[212:213], 1.0 op_sel_hi:[1,1,0] neg_lo:[1,0,0] neg_hi:[1,0,0]
	v_pk_fma_f32 v[130:131], v[218:219], v[130:131], 1.0 op_sel_hi:[1,1,0] neg_lo:[1,0,0] neg_hi:[1,0,0]
	v_bfi_b32 v204, s35, v212, v204
	v_bfi_b32 v214, s35, v130, v214
	v_bfi_b32 v205, s35, v213, v205
	v_bfi_b32 v215, s35, v131, v215
	v_pk_add_f32 v[204:205], v[204:205], 1.0 op_sel_hi:[1,0]
	v_pk_add_f32 v[214:215], v[214:215], 1.0 op_sel_hi:[1,0]
	v_pk_mul_f32 v[206:207], v[206:207], v[204:205]
	v_pk_mul_f32 v[216:217], v[216:217], v[214:215]
	v_cvt_pk_bf16_f32 v152, v206, v207
	v_cvt_pk_bf16_f32 v153, v216, v217
	ds_write_b64 v148, v[152:153]
	v_pk_add_f32 v[204:205], v[40:41], v[224:225]
	v_pk_add_f32 v[214:215], v[42:43], v[226:227]
	v_pk_mul_f32 v[206:207], v[204:205], 0.5 op_sel_hi:[1,0]
	v_pk_mul_f32 v[216:217], v[214:215], 0.5 op_sel_hi:[1,0]
	v_pk_mul_f32 v[204:205], v[204:205], s[50:51] op_sel_hi:[1,0]
	v_pk_mul_f32 v[214:215], v[214:215], s[50:51] op_sel_hi:[1,0]
	v_mul_f32_e64 v208, |v204|, -|v204|
	v_mul_f32_e64 v218, |v214|, -|v214|
	v_mul_f32_e64 v209, |v205|, -|v205|
	v_mul_f32_e64 v219, |v215|, -|v215|
	v_fma_f32 v210, |v204|, s78, 1.0
	v_fma_f32 v128, |v214|, s78, 1.0
	v_fma_f32 v211, |v205|, s78, 1.0
	v_fma_f32 v129, |v215|, s78, 1.0
	v_mul_f32_e32 v208, 0x3fb8aa3b, v208
	v_mul_f32_e32 v218, 0x3fb8aa3b, v218
	v_mul_f32_e32 v209, 0x3fb8aa3b, v209
	v_mul_f32_e32 v219, 0x3fb8aa3b, v219
	v_rcp_f32_e32 v210, v210
	v_rcp_f32_e32 v128, v128
	v_rcp_f32_e32 v211, v211
	v_rcp_f32_e32 v129, v129
	v_exp_f32_e32 v208, v208
	v_exp_f32_e32 v218, v218
	v_exp_f32_e32 v209, v209
	v_exp_f32_e32 v219, v219
	v_pk_fma_f32 v[212:213], v[210:211], s[86:87], v[244:245] op_sel_hi:[1,0,1]
	v_pk_fma_f32 v[130:131], v[128:129], s[86:87], v[244:245] op_sel_hi:[1,0,1]
	v_pk_fma_f32 v[212:213], v[212:213], v[210:211], s[88:89] op_sel_hi:[1,1,0]
	v_pk_fma_f32 v[130:131], v[130:131], v[128:129], s[88:89] op_sel_hi:[1,1,0]
	v_pk_fma_f32 v[212:213], v[212:213], v[210:211], s[90:91] op_sel_hi:[1,1,0]
	v_pk_fma_f32 v[130:131], v[130:131], v[128:129], s[90:91] op_sel_hi:[1,1,0]
	v_pk_fma_f32 v[212:213], v[212:213], v[210:211], s[96:97] op_sel_hi:[1,1,0]
	v_pk_fma_f32 v[130:131], v[130:131], v[128:129], s[96:97] op_sel_hi:[1,1,0]
	v_pk_mul_f32 v[212:213], v[210:211], v[212:213]
	v_pk_mul_f32 v[130:131], v[128:129], v[130:131]
	v_pk_fma_f32 v[212:213], v[208:209], v[212:213], 1.0 op_sel_hi:[1,1,0] neg_lo:[1,0,0] neg_hi:[1,0,0]
	v_pk_fma_f32 v[130:131], v[218:219], v[130:131], 1.0 op_sel_hi:[1,1,0] neg_lo:[1,0,0] neg_hi:[1,0,0]
	v_bfi_b32 v204, s35, v212, v204
	v_bfi_b32 v214, s35, v130, v214
	v_bfi_b32 v205, s35, v213, v205
	v_bfi_b32 v215, s35, v131, v215
	v_pk_add_f32 v[204:205], v[204:205], 1.0 op_sel_hi:[1,0]
	v_pk_add_f32 v[214:215], v[214:215], 1.0 op_sel_hi:[1,0]
	v_pk_mul_f32 v[206:207], v[206:207], v[204:205]
	v_pk_mul_f32 v[216:217], v[216:217], v[214:215]
	v_cvt_pk_bf16_f32 v154, v206, v207
	v_cvt_pk_bf16_f32 v155, v216, v217
	ds_write_b64 v149, v[154:155]
	v_pk_add_f32 v[204:205], v[36:37], v[228:229]
	v_pk_add_f32 v[214:215], v[38:39], v[230:231]
	v_pk_mul_f32 v[206:207], v[204:205], 0.5 op_sel_hi:[1,0]
	v_pk_mul_f32 v[216:217], v[214:215], 0.5 op_sel_hi:[1,0]
	v_pk_mul_f32 v[204:205], v[204:205], s[50:51] op_sel_hi:[1,0]
	v_pk_mul_f32 v[214:215], v[214:215], s[50:51] op_sel_hi:[1,0]
	v_mul_f32_e64 v208, |v204|, -|v204|
	v_mul_f32_e64 v218, |v214|, -|v214|
	v_mul_f32_e64 v209, |v205|, -|v205|
	v_mul_f32_e64 v219, |v215|, -|v215|
	v_fma_f32 v210, |v204|, s78, 1.0
	v_fma_f32 v128, |v214|, s78, 1.0
	v_fma_f32 v211, |v205|, s78, 1.0
	v_fma_f32 v129, |v215|, s78, 1.0
	v_mul_f32_e32 v208, 0x3fb8aa3b, v208
	v_mul_f32_e32 v218, 0x3fb8aa3b, v218
	v_mul_f32_e32 v209, 0x3fb8aa3b, v209
	v_mul_f32_e32 v219, 0x3fb8aa3b, v219
	v_rcp_f32_e32 v210, v210
	v_rcp_f32_e32 v128, v128
	v_rcp_f32_e32 v211, v211
	v_rcp_f32_e32 v129, v129
	v_exp_f32_e32 v208, v208
	v_exp_f32_e32 v218, v218
	v_exp_f32_e32 v209, v209
	v_exp_f32_e32 v219, v219
	v_pk_fma_f32 v[212:213], v[210:211], s[86:87], v[244:245] op_sel_hi:[1,0,1]
	v_pk_fma_f32 v[130:131], v[128:129], s[86:87], v[244:245] op_sel_hi:[1,0,1]
	v_pk_fma_f32 v[212:213], v[212:213], v[210:211], s[88:89] op_sel_hi:[1,1,0]
	v_pk_fma_f32 v[130:131], v[130:131], v[128:129], s[88:89] op_sel_hi:[1,1,0]
	v_pk_fma_f32 v[212:213], v[212:213], v[210:211], s[90:91] op_sel_hi:[1,1,0]
	v_pk_fma_f32 v[130:131], v[130:131], v[128:129], s[90:91] op_sel_hi:[1,1,0]
	v_pk_fma_f32 v[212:213], v[212:213], v[210:211], s[96:97] op_sel_hi:[1,1,0]
	v_pk_fma_f32 v[130:131], v[130:131], v[128:129], s[96:97] op_sel_hi:[1,1,0]
	v_pk_mul_f32 v[212:213], v[210:211], v[212:213]
	v_pk_mul_f32 v[130:131], v[128:129], v[130:131]
	v_pk_fma_f32 v[212:213], v[208:209], v[212:213], 1.0 op_sel_hi:[1,1,0] neg_lo:[1,0,0] neg_hi:[1,0,0]
	v_pk_fma_f32 v[130:131], v[218:219], v[130:131], 1.0 op_sel_hi:[1,1,0] neg_lo:[1,0,0] neg_hi:[1,0,0]
	v_bfi_b32 v204, s35, v212, v204
	v_bfi_b32 v214, s35, v130, v214
	v_bfi_b32 v205, s35, v213, v205
	v_bfi_b32 v215, s35, v131, v215
	v_pk_add_f32 v[204:205], v[204:205], 1.0 op_sel_hi:[1,0]
	v_pk_add_f32 v[214:215], v[214:215], 1.0 op_sel_hi:[1,0]
	v_pk_mul_f32 v[206:207], v[206:207], v[204:205]
	v_pk_mul_f32 v[216:217], v[216:217], v[214:215]
	v_cvt_pk_bf16_f32 v152, v206, v207
	v_cvt_pk_bf16_f32 v153, v216, v217
; __device__ __forceinline__ float erf_fast(float x) {
;   const float ax = fabsf(x);
;   const float t = __builtin_amdgcn_rcpf(fmaf(0.3275911f, ax, 1.0f));
;   float p = fmaf(1.061405429f, t, -1.453152027f);
;   p = fmaf(p, t, 1.421413741f); p = fmaf(p, t, -0.284496736f); p = fmaf(p, t, 0.254829592f);
;   const float e = 1.0f - p * t * __expf(-ax * ax);
;   return copysignf(e, x);
; }
; template <int MODE> __device__ __forceinline__ void epi_store(const GemmDesc& g, int row, int col, f32x4 v) {
;     ...
;     case E_GELU: {
;       const float4 bb = *(const float4*)(g.b0 + col);
;       float t[4] = {v[0] + bb.x, v[1] + bb.y, v[2] + bb.z, v[3] + bb.w};
; #pragma unroll
;       for (int i = 0; i < 4; ++i) t[i] = 0.5f * t[i] * (1.0f + erf_fast(t[i] * 0.70710678118654752f));
;       uint2 o; o.x = pack2(t[0], t[1]); o.y = pack2(t[2], t[3]);
;       *(uint2*)((u16*)g.o0 + (size_t)row * g.ldo + col) = o;
;     } break;
	ds_write_b64 v150, v[152:153]
	v_pk_add_f32 v[204:205], v[32:33], v[232:233]
	v_pk_add_f32 v[214:215], v[34:35], v[234:235]
	v_pk_mul_f32 v[206:207], v[204:205], 0.5 op_sel_hi:[1,0]
	v_pk_mul_f32 v[216:217], v[214:215], 0.5 op_sel_hi:[1,0]
	v_pk_mul_f32 v[204:205], v[204:205], s[50:51] op_sel_hi:[1,0]
	v_pk_mul_f32 v[214:215], v[214:215], s[50:51] op_sel_hi:[1,0]
	v_mul_f32_e64 v208, |v204|, -|v204|
	v_mul_f32_e64 v218, |v214|, -|v214|
	v_mul_f32_e64 v209, |v205|, -|v205|
	v_mul_f32_e64 v219, |v215|, -|v215|
	v_fma_f32 v210, |v204|, s78, 1.0
	v_fma_f32 v128, |v214|, s78, 1.0
	v_fma_f32 v211, |v205|, s78, 1.0
	v_fma_f32 v129, |v215|, s78, 1.0
	v_mul_f32_e32 v208, 0x3fb8aa3b, v208
	v_mul_f32_e32 v218, 0x3fb8aa3b, v218
	v_mul_f32_e32 v209, 0x3fb8aa3b, v209
	v_mul_f32_e32 v219, 0x3fb8aa3b, v219
	v_rcp_f32_e32 v210, v210
	v_rcp_f32_e32 v128, v128
	v_rcp_f32_e32 v211, v211
	v_rcp_f32_e32 v129, v129
	v_exp_f32_e32 v208, v208
	v_exp_f32_e32 v218, v218
	v_exp_f32_e32 v209, v209
	v_exp_f32_e32 v219, v219
	v_pk_fma_f32 v[212:213], v[210:211], s[86:87], v[244:245] op_sel_hi:[1,0,1]
	v_pk_fma_f32 v[130:131], v[128:129], s[86:87], v[244:245] op_sel_hi:[1,0,1]
	v_pk_fma_f32 v[212:213], v[212:213], v[210:211], s[88:89] op_sel_hi:[1,1,0]
	v_pk_fma_f32 v[130:131], v[130:131], v[128:129], s[88:89] op_sel_hi:[1,1,0]
	v_pk_fma_f32 v[212:213], v[212:213], v[210:211], s[90:91] op_sel_hi:[1,1,0]
	v_pk_fma_f32 v[130:131], v[130:131], v[128:129], s[90:91] op_sel_hi:[1,1,0]
	v_pk_fma_f32 v[212:213], v[212:213], v[210:211], s[96:97] op_sel_hi:[1,1,0]
	v_pk_fma_f32 v[130:131], v[130:131], v[128:129], s[96:97] op_sel_hi:[1,1,0]
	v_pk_mul_f32 v[212:213], v[210:211], v[212:213]
	v_pk_mul_f32 v[130:131], v[128:129], v[130:131]
	v_pk_fma_f32 v[212:213], v[208:209], v[212:213], 1.0 op_sel_hi:[1,1,0] neg_lo:[1,0,0] neg_hi:[1,0,0]
	v_pk_fma_f32 v[130:131], v[218:219], v[130:131], 1.0 op_sel_hi:[1,1,0] neg_lo:[1,0,0] neg_hi:[1,0,0]
	v_bfi_b32 v204, s35, v212, v204
	v_bfi_b32 v214, s35, v130, v214
	v_bfi_b32 v205, s35, v213, v205
	v_bfi_b32 v215, s35, v131, v215
	v_pk_add_f32 v[204:205], v[204:205], 1.0 op_sel_hi:[1,0]
	v_pk_add_f32 v[214:215], v[214:215], 1.0 op_sel_hi:[1,0]
	v_pk_mul_f32 v[206:207], v[206:207], v[204:205]
	v_pk_mul_f32 v[216:217], v[216:217], v[214:215]
	v_cvt_pk_bf16_f32 v154, v206, v207
	v_cvt_pk_bf16_f32 v155, v216, v217
	ds_write_b64 v151, v[154:155]
	s_waitcnt lgkmcnt(4)
	global_store_dwordx4 v146, v[236:239], s[66:67]
	global_store_dwordx4 v147, v[240:243], s[66:67]
	v_add_u32_e32 v146, s5, v146
	v_add_u32_e32 v147, s5, v147
	ds_read_b128 v[236:239], v156
	ds_read_b128 v[240:243], v156 offset:1024
	v_pk_add_f32 v[204:205], v[28:29], v[220:221]
	v_pk_add_f32 v[214:215], v[30:31], v[222:223]
	v_pk_mul_f32 v[206:207], v[204:205], 0.5 op_sel_hi:[1,0]
	v_pk_mul_f32 v[216:217], v[214:215], 0.5 op_sel_hi:[1,0]
	v_pk_mul_f32 v[204:205], v[204:205], s[50:51] op_sel_hi:[1,0]
	v_pk_mul_f32 v[214:215], v[214:215], s[50:51] op_sel_hi:[1,0]
	v_mul_f32_e64 v208, |v204|, -|v204|
	v_mul_f32_e64 v218, |v214|, -|v214|
	v_mul_f32_e64 v209, |v205|, -|v205|
	v_mul_f32_e64 v219, |v215|, -|v215|
	v_fma_f32 v210, |v204|, s78, 1.0
	v_fma_f32 v128, |v214|, s78, 1.0
	v_fma_f32 v211, |v205|, s78, 1.0
	v_fma_f32 v129, |v215|, s78, 1.0
	v_mul_f32_e32 v208, 0x3fb8aa3b, v208
	v_mul_f32_e32 v218, 0x3fb8aa3b, v218
	v_mul_f32_e32 v209, 0x3fb8aa3b, v209
	v_mul_f32_e32 v219, 0x3fb8aa3b, v219
	v_rcp_f32_e32 v210, v210
	v_rcp_f32_e32 v128, v128
	v_rcp_f32_e32 v211, v211
	v_rcp_f32_e32 v129, v129
	v_exp_f32_e32 v208, v208
	v_exp_f32_e32 v218, v218
	v_exp_f32_e32 v209, v209
	v_exp_f32_e32 v219, v219
	v_pk_fma_f32 v[212:213], v[210:211], s[86:87], v[244:245] op_sel_hi:[1,0,1]
	v_pk_fma_f32 v[130:131], v[128:129], s[86:87], v[244:245] op_sel_hi:[1,0,1]
	v_pk_fma_f32 v[212:213], v[212:213], v[210:211], s[88:89] op_sel_hi:[1,1,0]
	v_pk_fma_f32 v[130:131], v[130:131], v[128:129], s[88:89] op_sel_hi:[1,1,0]
	v_pk_fma_f32 v[212:213], v[212:213], v[210:211], s[90:91] op_sel_hi:[1,1,0]
	v_pk_fma_f32 v[130:131], v[130:131], v[128:129], s[90:91] op_sel_hi:[1,1,0]
	v_pk_fma_f32 v[212:213], v[212:213], v[210:211], s[96:97] op_sel_hi:[1,1,0]
	v_pk_fma_f32 v[130:131], v[130:131], v[128:129], s[96:97] op_sel_hi:[1,1,0]
	v_pk_mul_f32 v[212:213], v[210:211], v[212:213]
	v_pk_mul_f32 v[130:131], v[128:129], v[130:131]
	v_pk_fma_f32 v[212:213], v[208:209], v[212:213], 1.0 op_sel_hi:[1,1,0] neg_lo:[1,0,0] neg_hi:[1,0,0]
	v_pk_fma_f32 v[130:131], v[218:219], v[130:131], 1.0 op_sel_hi:[1,1,0] neg_lo:[1,0,0] neg_hi:[1,0,0]
	v_bfi_b32 v204, s35, v212, v204
	v_bfi_b32 v214, s35, v130, v214
	v_bfi_b32 v205, s35, v213, v205
	v_bfi_b32 v215, s35, v131, v215
	v_pk_add_f32 v[204:205], v[204:205], 1.0 op_sel_hi:[1,0]
	v_pk_add_f32 v[214:215], v[214:215], 1.0 op_sel_hi:[1,0]
	v_pk_mul_f32 v[206:207], v[206:207], v[204:205]
	v_pk_mul_f32 v[216:217], v[216:217], v[214:215]
	v_cvt_pk_bf16_f32 v152, v206, v207
	v_cvt_pk_bf16_f32 v153, v216, v217
	ds_write_b64 v148, v[152:153]
	v_pk_add_f32 v[204:205], v[24:25], v[224:225]
	v_pk_add_f32 v[214:215], v[26:27], v[226:227]
	v_pk_mul_f32 v[206:207], v[204:205], 0.5 op_sel_hi:[1,0]
	v_pk_mul_f32 v[216:217], v[214:215], 0.5 op_sel_hi:[1,0]
	v_pk_mul_f32 v[204:205], v[204:205], s[50:51] op_sel_hi:[1,0]
	v_pk_mul_f32 v[214:215], v[214:215], s[50:51] op_sel_hi:[1,0]
	v_mul_f32_e64 v208, |v204|, -|v204|
	v_mul_f32_e64 v218, |v214|, -|v214|
	v_mul_f32_e64 v209, |v205|, -|v205|
	v_mul_f32_e64 v219, |v215|, -|v215|
	v_fma_f32 v210, |v204|, s78, 1.0
	v_fma_f32 v128, |v214|, s78, 1.0
	v_fma_f32 v211, |v205|, s78, 1.0
	v_fma_f32 v129, |v215|, s78, 1.0
	v_mul_f32_e32 v208, 0x3fb8aa3b, v208
; __device__ __forceinline__ float erf_fast(float x) {
;   const float ax = fabsf(x);
;   const float t = __builtin_amdgcn_rcpf(fmaf(0.3275911f, ax, 1.0f));
;   float p = fmaf(1.061405429f, t, -1.453152027f);
;   p = fmaf(p, t, 1.421413741f); p = fmaf(p, t, -0.284496736f); p = fmaf(p, t, 0.254829592f);
;   const float e = 1.0f - p * t * __expf(-ax * ax);
;   return copysignf(e, x);
; }
; template <int MODE> __device__ __forceinline__ void epi_store(const GemmDesc& g, int row, int col, f32x4 v) {
;     ...
;     case E_GELU: {
;       const float4 bb = *(const float4*)(g.b0 + col);
;       float t[4] = {v[0] + bb.x, v[1] + bb.y, v[2] + bb.z, v[3] + bb.w};
; #pragma unroll
;       for (int i = 0; i < 4; ++i) t[i] = 0.5f * t[i] * (1.0f + erf_fast(t[i] * 0.70710678118654752f));
;       uint2 o; o.x = pack2(t[0], t[1]); o.y = pack2(t[2], t[3]);
;       *(uint2*)((u16*)g.o0 + (size_t)row * g.ldo + col) = o;
;     } break;
	v_mul_f32_e32 v218, 0x3fb8aa3b, v218
	v_mul_f32_e32 v209, 0x3fb8aa3b, v209
	v_mul_f32_e32 v219, 0x3fb8aa3b, v219
	v_rcp_f32_e32 v210, v210
	v_rcp_f32_e32 v128, v128
	v_rcp_f32_e32 v211, v211
	v_rcp_f32_e32 v129, v129
	v_exp_f32_e32 v208, v208
	v_exp_f32_e32 v218, v218
	v_exp_f32_e32 v209, v209
	v_exp_f32_e32 v219, v219
	v_pk_fma_f32 v[212:213], v[210:211], s[86:87], v[244:245] op_sel_hi:[1,0,1]
	v_pk_fma_f32 v[130:131], v[128:129], s[86:87], v[244:245] op_sel_hi:[1,0,1]
	v_pk_fma_f32 v[212:213], v[212:213], v[210:211], s[88:89] op_sel_hi:[1,1,0]
	v_pk_fma_f32 v[130:131], v[130:131], v[128:129], s[88:89] op_sel_hi:[1,1,0]
	v_pk_fma_f32 v[212:213], v[212:213], v[210:211], s[90:91] op_sel_hi:[1,1,0]
	v_pk_fma_f32 v[130:131], v[130:131], v[128:129], s[90:91] op_sel_hi:[1,1,0]
	v_pk_fma_f32 v[212:213], v[212:213], v[210:211], s[96:97] op_sel_hi:[1,1,0]
	v_pk_fma_f32 v[130:131], v[130:131], v[128:129], s[96:97] op_sel_hi:[1,1,0]
	v_pk_mul_f32 v[212:213], v[210:211], v[212:213]
	v_pk_mul_f32 v[130:131], v[128:129], v[130:131]
	v_pk_fma_f32 v[212:213], v[208:209], v[212:213], 1.0 op_sel_hi:[1,1,0] neg_lo:[1,0,0] neg_hi:[1,0,0]
	v_pk_fma_f32 v[130:131], v[218:219], v[130:131], 1.0 op_sel_hi:[1,1,0] neg_lo:[1,0,0] neg_hi:[1,0,0]
	v_bfi_b32 v204, s35, v212, v204
	v_bfi_b32 v214, s35, v130, v214
	v_bfi_b32 v205, s35, v213, v205
	v_bfi_b32 v215, s35, v131, v215
	v_pk_add_f32 v[204:205], v[204:205], 1.0 op_sel_hi:[1,0]
	v_pk_add_f32 v[214:215], v[214:215], 1.0 op_sel_hi:[1,0]
	v_pk_mul_f32 v[206:207], v[206:207], v[204:205]
	v_pk_mul_f32 v[216:217], v[216:217], v[214:215]
	v_cvt_pk_bf16_f32 v154, v206, v207
	v_cvt_pk_bf16_f32 v155, v216, v217
	ds_write_b64 v149, v[154:155]
	v_pk_add_f32 v[204:205], v[20:21], v[228:229]
	v_pk_add_f32 v[214:215], v[22:23], v[230:231]
	v_pk_mul_f32 v[206:207], v[204:205], 0.5 op_sel_hi:[1,0]
	v_pk_mul_f32 v[216:217], v[214:215], 0.5 op_sel_hi:[1,0]
	v_pk_mul_f32 v[204:205], v[204:205], s[50:51] op_sel_hi:[1,0]
	v_pk_mul_f32 v[214:215], v[214:215], s[50:51] op_sel_hi:[1,0]
	v_mul_f32_e64 v208, |v204|, -|v204|
	v_mul_f32_e64 v218, |v214|, -|v214|
	v_mul_f32_e64 v209, |v205|, -|v205|
	v_mul_f32_e64 v219, |v215|, -|v215|
	v_fma_f32 v210, |v204|, s78, 1.0
	v_fma_f32 v128, |v214|, s78, 1.0
	v_fma_f32 v211, |v205|, s78, 1.0
	v_fma_f32 v129, |v215|, s78, 1.0
	v_mul_f32_e32 v208, 0x3fb8aa3b, v208
	v_mul_f32_e32 v218, 0x3fb8aa3b, v218
	v_mul_f32_e32 v209, 0x3fb8aa3b, v209
	v_mul_f32_e32 v219, 0x3fb8aa3b, v219
	v_rcp_f32_e32 v210, v210
	v_rcp_f32_e32 v128, v128
	v_rcp_f32_e32 v211, v211
	v_rcp_f32_e32 v129, v129
	v_exp_f32_e32 v208, v208
	v_exp_f32_e32 v218, v218
	v_exp_f32_e32 v209, v209
	v_exp_f32_e32 v219, v219
	v_pk_fma_f32 v[212:213], v[210:211], s[86:87], v[244:245] op_sel_hi:[1,0,1]
	v_pk_fma_f32 v[130:131], v[128:129], s[86:87], v[244:245] op_sel_hi:[1,0,1]
	v_pk_fma_f32 v[212:213], v[212:213], v[210:211], s[88:89] op_sel_hi:[1,1,0]
	v_pk_fma_f32 v[130:131], v[130:131], v[128:129], s[88:89] op_sel_hi:[1,1,0]
	v_pk_fma_f32 v[212:213], v[212:213], v[210:211], s[90:91] op_sel_hi:[1,1,0]
	v_pk_fma_f32 v[130:131], v[130:131], v[128:129], s[90:91] op_sel_hi:[1,1,0]
	v_pk_fma_f32 v[212:213], v[212:213], v[210:211], s[96:97] op_sel_hi:[1,1,0]
	v_pk_fma_f32 v[130:131], v[130:131], v[128:129], s[96:97] op_sel_hi:[1,1,0]
	v_pk_mul_f32 v[212:213], v[210:211], v[212:213]
	v_pk_mul_f32 v[130:131], v[128:129], v[130:131]
	v_pk_fma_f32 v[212:213], v[208:209], v[212:213], 1.0 op_sel_hi:[1,1,0] neg_lo:[1,0,0] neg_hi:[1,0,0]
	v_pk_fma_f32 v[130:131], v[218:219], v[130:131], 1.0 op_sel_hi:[1,1,0] neg_lo:[1,0,0] neg_hi:[1,0,0]
	v_bfi_b32 v204, s35, v212, v204
	v_bfi_b32 v214, s35, v130, v214
	v_bfi_b32 v205, s35, v213, v205
	v_bfi_b32 v215, s35, v131, v215
	v_pk_add_f32 v[204:205], v[204:205], 1.0 op_sel_hi:[1,0]
	v_pk_add_f32 v[214:215], v[214:215], 1.0 op_sel_hi:[1,0]
	v_pk_mul_f32 v[206:207], v[206:207], v[204:205]
	v_pk_mul_f32 v[216:217], v[216:217], v[214:215]
	v_cvt_pk_bf16_f32 v152, v206, v207
	v_cvt_pk_bf16_f32 v153, v216, v217
	ds_write_b64 v150, v[152:153]
	v_pk_add_f32 v[204:205], v[16:17], v[232:233]
	v_pk_add_f32 v[214:215], v[18:19], v[234:235]
	v_pk_mul_f32 v[206:207], v[204:205], 0.5 op_sel_hi:[1,0]
	v_pk_mul_f32 v[216:217], v[214:215], 0.5 op_sel_hi:[1,0]
	v_pk_mul_f32 v[204:205], v[204:205], s[50:51] op_sel_hi:[1,0]
	v_pk_mul_f32 v[214:215], v[214:215], s[50:51] op_sel_hi:[1,0]
	v_mul_f32_e64 v208, |v204|, -|v204|
	v_mul_f32_e64 v218, |v214|, -|v214|
	v_mul_f32_e64 v209, |v205|, -|v205|
	v_mul_f32_e64 v219, |v215|, -|v215|
	v_fma_f32 v210, |v204|, s78, 1.0
	v_fma_f32 v128, |v214|, s78, 1.0
	v_fma_f32 v211, |v205|, s78, 1.0
	v_fma_f32 v129, |v215|, s78, 1.0
	v_mul_f32_e32 v208, 0x3fb8aa3b, v208
	v_mul_f32_e32 v218, 0x3fb8aa3b, v218
	v_mul_f32_e32 v209, 0x3fb8aa3b, v209
	v_mul_f32_e32 v219, 0x3fb8aa3b, v219
	v_rcp_f32_e32 v210, v210
	v_rcp_f32_e32 v128, v128
	v_rcp_f32_e32 v211, v211
	v_rcp_f32_e32 v129, v129
	v_exp_f32_e32 v208, v208
	v_exp_f32_e32 v218, v218
	v_exp_f32_e32 v209, v209
	v_exp_f32_e32 v219, v219
	v_pk_fma_f32 v[212:213], v[210:211], s[86:87], v[244:245] op_sel_hi:[1,0,1]
	v_pk_fma_f32 v[130:131], v[128:129], s[86:87], v[244:245] op_sel_hi:[1,0,1]
	v_pk_fma_f32 v[212:213], v[212:213], v[210:211], s[88:89] op_sel_hi:[1,1,0]
	v_pk_fma_f32 v[130:131], v[130:131], v[128:129], s[88:89] op_sel_hi:[1,1,0]
	v_pk_fma_f32 v[212:213], v[212:213], v[210:211], s[90:91] op_sel_hi:[1,1,0]
	v_pk_fma_f32 v[130:131], v[130:131], v[128:129], s[90:91] op_sel_hi:[1,1,0]
	v_pk_fma_f32 v[212:213], v[212:213], v[210:211], s[96:97] op_sel_hi:[1,1,0]
	v_pk_fma_f32 v[130:131], v[130:131], v[128:129], s[96:97] op_sel_hi:[1,1,0]
	v_pk_mul_f32 v[212:213], v[210:211], v[212:213]
	v_pk_mul_f32 v[130:131], v[128:129], v[130:131]
	v_pk_fma_f32 v[212:213], v[208:209], v[212:213], 1.0 op_sel_hi:[1,1,0] neg_lo:[1,0,0] neg_hi:[1,0,0]
	v_pk_fma_f32 v[130:131], v[218:219], v[130:131], 1.0 op_sel_hi:[1,1,0] neg_lo:[1,0,0] neg_hi:[1,0,0]
	v_bfi_b32 v204, s35, v212, v204
	v_bfi_b32 v214, s35, v130, v214
	v_bfi_b32 v205, s35, v213, v205
	v_bfi_b32 v215, s35, v131, v215
	v_pk_add_f32 v[204:205], v[204:205], 1.0 op_sel_hi:[1,0]
	v_pk_add_f32 v[214:215], v[214:215], 1.0 op_sel_hi:[1,0]
	v_pk_mul_f32 v[206:207], v[206:207], v[204:205]
	v_pk_mul_f32 v[216:217], v[216:217], v[214:215]
	v_cvt_pk_bf16_f32 v154, v206, v207
	v_cvt_pk_bf16_f32 v155, v216, v217
	ds_write_b64 v151, v[154:155]
	s_waitcnt lgkmcnt(4)
; __device__ __forceinline__ float erf_fast(float x) {
;   const float ax = fabsf(x);
;   const float t = __builtin_amdgcn_rcpf(fmaf(0.3275911f, ax, 1.0f));
;   float p = fmaf(1.061405429f, t, -1.453152027f);
;   p = fmaf(p, t, 1.421413741f); p = fmaf(p, t, -0.284496736f); p = fmaf(p, t, 0.254829592f);
;   const float e = 1.0f - p * t * __expf(-ax * ax);
;   return copysignf(e, x);
; }
; template <int MODE> __device__ __forceinline__ void epi_store(const GemmDesc& g, int row, int col, f32x4 v) {
;     ...
;     case E_GELU: {
;       const float4 bb = *(const float4*)(g.b0 + col);
;       float t[4] = {v[0] + bb.x, v[1] + bb.y, v[2] + bb.z, v[3] + bb.w};
; #pragma unroll
;       for (int i = 0; i < 4; ++i) t[i] = 0.5f * t[i] * (1.0f + erf_fast(t[i] * 0.70710678118654752f));
;       uint2 o; o.x = pack2(t[0], t[1]); o.y = pack2(t[2], t[3]);
;       *(uint2*)((u16*)g.o0 + (size_t)row * g.ldo + col) = o;
;     } break;
	global_store_dwordx4 v146, v[236:239], s[66:67]
	global_store_dwordx4 v147, v[240:243], s[66:67]
	v_add_u32_e32 v146, s5, v146
	v_add_u32_e32 v147, s5, v147
	ds_read_b128 v[236:239], v156
	ds_read_b128 v[240:243], v156 offset:1024
	v_pk_add_f32 v[204:205], v[12:13], v[220:221]
	v_pk_add_f32 v[214:215], v[14:15], v[222:223]
	v_pk_mul_f32 v[206:207], v[204:205], 0.5 op_sel_hi:[1,0]
	v_pk_mul_f32 v[216:217], v[214:215], 0.5 op_sel_hi:[1,0]
	v_pk_mul_f32 v[204:205], v[204:205], s[50:51] op_sel_hi:[1,0]
	v_pk_mul_f32 v[214:215], v[214:215], s[50:51] op_sel_hi:[1,0]
	v_mul_f32_e64 v208, |v204|, -|v204|
	v_mul_f32_e64 v218, |v214|, -|v214|
	v_mul_f32_e64 v209, |v205|, -|v205|
	v_mul_f32_e64 v219, |v215|, -|v215|
	v_fma_f32 v210, |v204|, s78, 1.0
	v_fma_f32 v128, |v214|, s78, 1.0
	v_fma_f32 v211, |v205|, s78, 1.0
	v_fma_f32 v129, |v215|, s78, 1.0
	v_mul_f32_e32 v208, 0x3fb8aa3b, v208
	v_mul_f32_e32 v218, 0x3fb8aa3b, v218
	v_mul_f32_e32 v209, 0x3fb8aa3b, v209
	v_mul_f32_e32 v219, 0x3fb8aa3b, v219
	v_rcp_f32_e32 v210, v210
	v_rcp_f32_e32 v128, v128
	v_rcp_f32_e32 v211, v211
	v_rcp_f32_e32 v129, v129
	v_exp_f32_e32 v208, v208
	v_exp_f32_e32 v218, v218
	v_exp_f32_e32 v209, v209
	v_exp_f32_e32 v219, v219
	v_pk_fma_f32 v[212:213], v[210:211], s[86:87], v[244:245] op_sel_hi:[1,0,1]
	v_pk_fma_f32 v[130:131], v[128:129], s[86:87], v[244:245] op_sel_hi:[1,0,1]
	v_pk_fma_f32 v[212:213], v[212:213], v[210:211], s[88:89] op_sel_hi:[1,1,0]
	v_pk_fma_f32 v[130:131], v[130:131], v[128:129], s[88:89] op_sel_hi:[1,1,0]
	v_pk_fma_f32 v[212:213], v[212:213], v[210:211], s[90:91] op_sel_hi:[1,1,0]
	v_pk_fma_f32 v[130:131], v[130:131], v[128:129], s[90:91] op_sel_hi:[1,1,0]
	v_pk_fma_f32 v[212:213], v[212:213], v[210:211], s[96:97] op_sel_hi:[1,1,0]
	v_pk_fma_f32 v[130:131], v[130:131], v[128:129], s[96:97] op_sel_hi:[1,1,0]
	v_pk_mul_f32 v[212:213], v[210:211], v[212:213]
	v_pk_mul_f32 v[130:131], v[128:129], v[130:131]
	v_pk_fma_f32 v[212:213], v[208:209], v[212:213], 1.0 op_sel_hi:[1,1,0] neg_lo:[1,0,0] neg_hi:[1,0,0]
	v_pk_fma_f32 v[130:131], v[218:219], v[130:131], 1.0 op_sel_hi:[1,1,0] neg_lo:[1,0,0] neg_hi:[1,0,0]
	v_bfi_b32 v204, s35, v212, v204
	v_bfi_b32 v214, s35, v130, v214
	v_bfi_b32 v205, s35, v213, v205
	v_bfi_b32 v215, s35, v131, v215
	v_pk_add_f32 v[204:205], v[204:205], 1.0 op_sel_hi:[1,0]
	v_pk_add_f32 v[214:215], v[214:215], 1.0 op_sel_hi:[1,0]
	v_pk_mul_f32 v[206:207], v[206:207], v[204:205]
	v_pk_mul_f32 v[216:217], v[216:217], v[214:215]
	v_cvt_pk_bf16_f32 v152, v206, v207
	v_cvt_pk_bf16_f32 v153, v216, v217
	ds_write_b64 v148, v[152:153]
	v_pk_add_f32 v[204:205], v[8:9], v[224:225]
	v_pk_add_f32 v[214:215], v[10:11], v[226:227]
	v_pk_mul_f32 v[206:207], v[204:205], 0.5 op_sel_hi:[1,0]
	v_pk_mul_f32 v[216:217], v[214:215], 0.5 op_sel_hi:[1,0]
	v_pk_mul_f32 v[204:205], v[204:205], s[50:51] op_sel_hi:[1,0]
	v_pk_mul_f32 v[214:215], v[214:215], s[50:51] op_sel_hi:[1,0]
	v_mul_f32_e64 v208, |v204|, -|v204|
	v_mul_f32_e64 v218, |v214|, -|v214|
	v_mul_f32_e64 v209, |v205|, -|v205|
	v_mul_f32_e64 v219, |v215|, -|v215|
	v_fma_f32 v210, |v204|, s78, 1.0
	v_fma_f32 v128, |v214|, s78, 1.0
	v_fma_f32 v211, |v205|, s78, 1.0
	v_fma_f32 v129, |v215|, s78, 1.0
	v_mul_f32_e32 v208, 0x3fb8aa3b, v208
	v_mul_f32_e32 v218, 0x3fb8aa3b, v218
	v_mul_f32_e32 v209, 0x3fb8aa3b, v209
	v_mul_f32_e32 v219, 0x3fb8aa3b, v219
	v_rcp_f32_e32 v210, v210
	v_rcp_f32_e32 v128, v128
	v_rcp_f32_e32 v211, v211
	v_rcp_f32_e32 v129, v129
	v_exp_f32_e32 v208, v208
	v_exp_f32_e32 v218, v218
	v_exp_f32_e32 v209, v209
	v_exp_f32_e32 v219, v219
	v_pk_fma_f32 v[212:213], v[210:211], s[86:87], v[244:245] op_sel_hi:[1,0,1]
	v_pk_fma_f32 v[130:131], v[128:129], s[86:87], v[244:245] op_sel_hi:[1,0,1]
	v_pk_fma_f32 v[212:213], v[212:213], v[210:211], s[88:89] op_sel_hi:[1,1,0]
	v_pk_fma_f32 v[130:131], v[130:131], v[128:129], s[88:89] op_sel_hi:[1,1,0]
	v_pk_fma_f32 v[212:213], v[212:213], v[210:211], s[90:91] op_sel_hi:[1,1,0]
	v_pk_fma_f32 v[130:131], v[130:131], v[128:129], s[90:91] op_sel_hi:[1,1,0]
	v_pk_fma_f32 v[212:213], v[212:213], v[210:211], s[96:97] op_sel_hi:[1,1,0]
	v_pk_fma_f32 v[130:131], v[130:131], v[128:129], s[96:97] op_sel_hi:[1,1,0]
	v_pk_mul_f32 v[212:213], v[210:211], v[212:213]
	v_pk_mul_f32 v[130:131], v[128:129], v[130:131]
	v_pk_fma_f32 v[212:213], v[208:209], v[212:213], 1.0 op_sel_hi:[1,1,0] neg_lo:[1,0,0] neg_hi:[1,0,0]
	v_pk_fma_f32 v[130:131], v[218:219], v[130:131], 1.0 op_sel_hi:[1,1,0] neg_lo:[1,0,0] neg_hi:[1,0,0]
	v_bfi_b32 v204, s35, v212, v204
	v_bfi_b32 v214, s35, v130, v214
	v_bfi_b32 v205, s35, v213, v205
	v_bfi_b32 v215, s35, v131, v215
	v_pk_add_f32 v[204:205], v[204:205], 1.0 op_sel_hi:[1,0]
	v_pk_add_f32 v[214:215], v[214:215], 1.0 op_sel_hi:[1,0]
	v_pk_mul_f32 v[206:207], v[206:207], v[204:205]
	v_pk_mul_f32 v[216:217], v[216:217], v[214:215]
	v_cvt_pk_bf16_f32 v154, v206, v207
	v_cvt_pk_bf16_f32 v155, v216, v217
	ds_write_b64 v149, v[154:155]
	v_pk_add_f32 v[204:205], v[4:5], v[228:229]
	v_pk_add_f32 v[214:215], v[6:7], v[230:231]
; __device__ __forceinline__ float erf_fast(float x) {
;   const float ax = fabsf(x);
;   const float t = __builtin_amdgcn_rcpf(fmaf(0.3275911f, ax, 1.0f));
;   float p = fmaf(1.061405429f, t, -1.453152027f);
;   p = fmaf(p, t, 1.421413741f); p = fmaf(p, t, -0.284496736f); p = fmaf(p, t, 0.254829592f);
;   const float e = 1.0f - p * t * __expf(-ax * ax);
;   return copysignf(e, x);
; }
; template <int MODE> __device__ __forceinline__ void epi_store(const GemmDesc& g, int row, int col, f32x4 v) {
;     ...
;     case E_GELU: {
;       const float4 bb = *(const float4*)(g.b0 + col);
;       float t[4] = {v[0] + bb.x, v[1] + bb.y, v[2] + bb.z, v[3] + bb.w};
; #pragma unroll
;       for (int i = 0; i < 4; ++i) t[i] = 0.5f * t[i] * (1.0f + erf_fast(t[i] * 0.70710678118654752f));
;       uint2 o; o.x = pack2(t[0], t[1]); o.y = pack2(t[2], t[3]);
;       *(uint2*)((u16*)g.o0 + (size_t)row * g.ldo + col) = o;
;     } break;
	v_pk_mul_f32 v[206:207], v[204:205], 0.5 op_sel_hi:[1,0]
	v_pk_mul_f32 v[216:217], v[214:215], 0.5 op_sel_hi:[1,0]
	v_pk_mul_f32 v[204:205], v[204:205], s[50:51] op_sel_hi:[1,0]
	v_pk_mul_f32 v[214:215], v[214:215], s[50:51] op_sel_hi:[1,0]
	v_mul_f32_e64 v208, |v204|, -|v204|
	v_mul_f32_e64 v218, |v214|, -|v214|
	v_mul_f32_e64 v209, |v205|, -|v205|
	v_mul_f32_e64 v219, |v215|, -|v215|
	v_fma_f32 v210, |v204|, s78, 1.0
	v_fma_f32 v128, |v214|, s78, 1.0
	v_fma_f32 v211, |v205|, s78, 1.0
	v_fma_f32 v129, |v215|, s78, 1.0
	v_mul_f32_e32 v208, 0x3fb8aa3b, v208
	v_mul_f32_e32 v218, 0x3fb8aa3b, v218
	v_mul_f32_e32 v209, 0x3fb8aa3b, v209
	v_mul_f32_e32 v219, 0x3fb8aa3b, v219
	v_rcp_f32_e32 v210, v210
	v_rcp_f32_e32 v128, v128
	v_rcp_f32_e32 v211, v211
	v_rcp_f32_e32 v129, v129
	v_exp_f32_e32 v208, v208
	v_exp_f32_e32 v218, v218
	v_exp_f32_e32 v209, v209
	v_exp_f32_e32 v219, v219
	v_pk_fma_f32 v[212:213], v[210:211], s[86:87], v[244:245] op_sel_hi:[1,0,1]
	v_pk_fma_f32 v[130:131], v[128:129], s[86:87], v[244:245] op_sel_hi:[1,0,1]
	v_pk_fma_f32 v[212:213], v[212:213], v[210:211], s[88:89] op_sel_hi:[1,1,0]
	v_pk_fma_f32 v[130:131], v[130:131], v[128:129], s[88:89] op_sel_hi:[1,1,0]
	v_pk_fma_f32 v[212:213], v[212:213], v[210:211], s[90:91] op_sel_hi:[1,1,0]
	v_pk_fma_f32 v[130:131], v[130:131], v[128:129], s[90:91] op_sel_hi:[1,1,0]
	v_pk_fma_f32 v[212:213], v[212:213], v[210:211], s[96:97] op_sel_hi:[1,1,0]
	v_pk_fma_f32 v[130:131], v[130:131], v[128:129], s[96:97] op_sel_hi:[1,1,0]
	v_pk_mul_f32 v[212:213], v[210:211], v[212:213]
	v_pk_mul_f32 v[130:131], v[128:129], v[130:131]
	v_pk_fma_f32 v[212:213], v[208:209], v[212:213], 1.0 op_sel_hi:[1,1,0] neg_lo:[1,0,0] neg_hi:[1,0,0]
	v_pk_fma_f32 v[130:131], v[218:219], v[130:131], 1.0 op_sel_hi:[1,1,0] neg_lo:[1,0,0] neg_hi:[1,0,0]
	v_bfi_b32 v204, s35, v212, v204
	v_bfi_b32 v214, s35, v130, v214
	v_bfi_b32 v205, s35, v213, v205
	v_bfi_b32 v215, s35, v131, v215
	v_pk_add_f32 v[204:205], v[204:205], 1.0 op_sel_hi:[1,0]
	v_pk_add_f32 v[214:215], v[214:215], 1.0 op_sel_hi:[1,0]
	v_pk_mul_f32 v[206:207], v[206:207], v[204:205]
	v_pk_mul_f32 v[216:217], v[216:217], v[214:215]
	v_cvt_pk_bf16_f32 v152, v206, v207
	v_cvt_pk_bf16_f32 v153, v216, v217
	ds_write_b64 v150, v[152:153]
	v_pk_add_f32 v[204:205], v[0:1], v[232:233]
	v_pk_add_f32 v[214:215], v[2:3], v[234:235]
	v_pk_mul_f32 v[206:207], v[204:205], 0.5 op_sel_hi:[1,0]
	v_pk_mul_f32 v[216:217], v[214:215], 0.5 op_sel_hi:[1,0]
	v_pk_mul_f32 v[204:205], v[204:205], s[50:51] op_sel_hi:[1,0]
	v_pk_mul_f32 v[214:215], v[214:215], s[50:51] op_sel_hi:[1,0]
	v_mul_f32_e64 v208, |v204|, -|v204|
	v_mul_f32_e64 v218, |v214|, -|v214|
	v_mul_f32_e64 v209, |v205|, -|v205|
	v_mul_f32_e64 v219, |v215|, -|v215|
	v_fma_f32 v210, |v204|, s78, 1.0
	v_fma_f32 v128, |v214|, s78, 1.0
	v_fma_f32 v211, |v205|, s78, 1.0
	v_fma_f32 v129, |v215|, s78, 1.0
	v_mul_f32_e32 v208, 0x3fb8aa3b, v208
	v_mul_f32_e32 v218, 0x3fb8aa3b, v218
	v_mul_f32_e32 v209, 0x3fb8aa3b, v209
	v_mul_f32_e32 v219, 0x3fb8aa3b, v219
	v_rcp_f32_e32 v210, v210
	v_rcp_f32_e32 v128, v128
	v_rcp_f32_e32 v211, v211
	v_rcp_f32_e32 v129, v129
	v_exp_f32_e32 v208, v208
	v_exp_f32_e32 v218, v218
	v_exp_f32_e32 v209, v209
	v_exp_f32_e32 v219, v219
	v_pk_fma_f32 v[212:213], v[210:211], s[86:87], v[244:245] op_sel_hi:[1,0,1]
	v_pk_fma_f32 v[130:131], v[128:129], s[86:87], v[244:245] op_sel_hi:[1,0,1]
	v_pk_fma_f32 v[212:213], v[212:213], v[210:211], s[88:89] op_sel_hi:[1,1,0]
	v_pk_fma_f32 v[130:131], v[130:131], v[128:129], s[88:89] op_sel_hi:[1,1,0]
	v_pk_fma_f32 v[212:213], v[212:213], v[210:211], s[90:91] op_sel_hi:[1,1,0]
	v_pk_fma_f32 v[130:131], v[130:131], v[128:129], s[90:91] op_sel_hi:[1,1,0]
	v_pk_fma_f32 v[212:213], v[212:213], v[210:211], s[96:97] op_sel_hi:[1,1,0]
	v_pk_fma_f32 v[130:131], v[130:131], v[128:129], s[96:97] op_sel_hi:[1,1,0]
	v_pk_mul_f32 v[212:213], v[210:211], v[212:213]
	v_pk_mul_f32 v[130:131], v[128:129], v[130:131]
	v_pk_fma_f32 v[212:213], v[208:209], v[212:213], 1.0 op_sel_hi:[1,1,0] neg_lo:[1,0,0] neg_hi:[1,0,0]
	v_pk_fma_f32 v[130:131], v[218:219], v[130:131], 1.0 op_sel_hi:[1,1,0] neg_lo:[1,0,0] neg_hi:[1,0,0]
	v_bfi_b32 v204, s35, v212, v204
	v_bfi_b32 v214, s35, v130, v214
	v_bfi_b32 v205, s35, v213, v205
	v_bfi_b32 v215, s35, v131, v215
	v_pk_add_f32 v[204:205], v[204:205], 1.0 op_sel_hi:[1,0]
	v_pk_add_f32 v[214:215], v[214:215], 1.0 op_sel_hi:[1,0]
	v_pk_mul_f32 v[206:207], v[206:207], v[204:205]
	v_pk_mul_f32 v[216:217], v[216:217], v[214:215]
	v_cvt_pk_bf16_f32 v154, v206, v207
	v_cvt_pk_bf16_f32 v155, v216, v217
	ds_write_b64 v151, v[154:155]
	s_waitcnt lgkmcnt(4)
	global_store_dwordx4 v146, v[236:239], s[66:67]
	global_store_dwordx4 v147, v[240:243], s[66:67]
	v_add_u32_e32 v146, s5, v146
	v_add_u32_e32 v147, s5, v147
	ds_read_b128 v[236:239], v156
	ds_read_b128 v[240:243], v156 offset:1024
	s_waitcnt lgkmcnt(0)
	global_store_dwordx4 v146, v[236:239], s[66:67]
	global_store_dwordx4 v147, v[240:243], s[66:67]
	s_branch .LBB0_261

; #define EPI_LOOP(MODE) do { _Pragma("unroll") for (int m = 0; m < 8; ++m) _Pragma("unroll") for (int n = 0; n < 4; ++n) \
;         epi_store<MODE>(g, brow + wr * 128 + m * 16 + fr, bcol + wc * 64 + n * 16 + fq * 4, acc[m][n]); } while (0)
; template <int MODE> __device__ __forceinline__ void epi_store(const GemmDesc& g, int row, int col, f32x4 v) {
;     ...
;     case E_SQRELU: {
;       float a = fmaxf(v[0], 0.f), b = fmaxf(v[1], 0.f), c = fmaxf(v[2], 0.f), d = fmaxf(v[3], 0.f);
;       uint2 o; o.x = pack2(a * a, b * b); o.y = pack2(c * c, d * d);
;       *(uint2*)((u16*)g.o0 + (size_t)row * g.ldo + col) = o;
;     } break;
; __device__ __forceinline__ void gemm_run(const GemmDesc& g, char* shm) {
;     ...
;     switch (g.emode) {
;       case E_SQRELU: EPI_LOOP(E_SQRELU); break;
.LBB0_1032:
	s_andn2_b64 vcc, exec, s[4:5]
	s_cbranch_vccnz .LBB0_261
	v_add_u32_e32 v128, s39, v172
	v_or_b32_e32 v154, s38, v175
	s_mov_b64 s[4:5], -1
	s_cmp_lg_u32 s8, 1
	v_ashrrev_i32_e32 v129, 31, v128
	v_ashrrev_i32_e32 v155, 31, v154
	v_or_b32_e32 v152, 16, v128
	v_or_b32_e32 v150, 32, v128
	v_or_b32_e32 v148, 48, v128
	v_or_b32_e32 v146, 64, v128
	v_or_b32_e32 v144, 0x50, v128
	v_or_b32_e32 v130, 0x60, v128
	s_cbranch_scc0 .LBB0_1035
	v_and_b32_e32 v204, 63, v135
	v_and_b32_e32 v205, 15, v204
	v_lshrrev_b32_e32 v206, 4, v204
	v_lshrrev_b32_e32 v207, 3, v204
	v_and_b32_e32 v208, 7, v204
	v_lshrrev_b32_e32 v209, 8, v135
	v_bfe_u32 v210, v135, 6, 2
	v_lshrrev_b32_e32 v211, 6, v135
	v_lshlrev_b32_e32 v211, 11, v211
	v_add_u32_e32 v211, 0x20000, v211
	v_lshrrev_b32_e32 v212, 1, v206
	v_and_b32_e32 v213, 7, v205
	v_xor_b32_e32 v212, v212, v213
	v_lshlrev_b32_e32 v212, 4, v212
	v_and_b32_e32 v213, 1, v206
	v_lshl_add_u32 v212, v213, 3, v212
	v_lshl_add_u32 v212, v205, 7, v212
	v_add_u32_e32 v148, v211, v212
	v_xor_b32_e32 v149, 32, v148
	v_xor_b32_e32 v150, 64, v148
	v_xor_b32_e32 v151, 0x60, v148
	v_xor_b32_e32 v212, v208, v207
	v_lshlrev_b32_e32 v212, 4, v212
	v_lshl_add_u32 v212, v207, 7, v212
	v_add_u32_e32 v156, v211, v212
	v_lshl_add_u32 v212, v209, 7, v207
	v_add_u32_e32 v212, s39, v212
	v_lshlrev_b32_e32 v213, 3, v208
	v_lshl_add_u32 v213, v210, 6, v213
	v_add_u32_e32 v213, s38, v213
	v_mul_lo_u32 v212, v212, s94
	v_add_lshl_u32 v146, v212, v213, 1
	s_lshl_b32 s4, s94, 4
	s_lshl_b32 s5, s94, 5
	v_add_u32_e32 v147, s4, v146
	v_max_f32_e32 v212, 0, v124
	v_max_f32_e32 v213, 0, v125
	v_max_f32_e32 v214, 0, v126
	v_max_f32_e32 v215, 0, v127
	v_pk_mul_f32 v[212:213], v[212:213], v[212:213]
	v_pk_mul_f32 v[214:215], v[214:215], v[214:215]
	v_cvt_pk_bf16_f32 v204, v212, v213
	v_cvt_pk_bf16_f32 v205, v214, v215
	ds_write_b64 v148, v[204:205]
	v_max_f32_e32 v216, 0, v120
	v_max_f32_e32 v217, 0, v121
	v_max_f32_e32 v218, 0, v122
	v_max_f32_e32 v219, 0, v123
	v_pk_mul_f32 v[216:217], v[216:217], v[216:217]
	v_pk_mul_f32 v[218:219], v[218:219], v[218:219]
	v_cvt_pk_bf16_f32 v206, v216, v217
	v_cvt_pk_bf16_f32 v207, v218, v219
	ds_write_b64 v149, v[206:207]
	v_max_f32_e32 v212, 0, v116
	v_max_f32_e32 v213, 0, v117
	v_max_f32_e32 v214, 0, v118
	v_max_f32_e32 v215, 0, v119
	v_pk_mul_f32 v[212:213], v[212:213], v[212:213]
	v_pk_mul_f32 v[214:215], v[214:215], v[214:215]
	v_cvt_pk_bf16_f32 v208, v212, v213
	v_cvt_pk_bf16_f32 v209, v214, v215
	ds_write_b64 v150, v[208:209]
	v_max_f32_e32 v216, 0, v112
	v_max_f32_e32 v217, 0, v113
	v_max_f32_e32 v218, 0, v114
	v_max_f32_e32 v219, 0, v115
	v_pk_mul_f32 v[216:217], v[216:217], v[216:217]
	v_pk_mul_f32 v[218:219], v[218:219], v[218:219]
	v_cvt_pk_bf16_f32 v210, v216, v217
	v_cvt_pk_bf16_f32 v211, v218, v219
	ds_write_b64 v151, v[210:211]
	ds_read_b128 v[236:239], v156
	ds_read_b128 v[240:243], v156 offset:1024
	v_max_f32_e32 v212, 0, v108
	v_max_f32_e32 v213, 0, v109
	v_max_f32_e32 v214, 0, v110
	v_max_f32_e32 v215, 0, v111
	v_pk_mul_f32 v[212:213], v[212:213], v[212:213]
	v_pk_mul_f32 v[214:215], v[214:215], v[214:215]
	v_cvt_pk_bf16_f32 v204, v212, v213
	v_cvt_pk_bf16_f32 v205, v214, v215
	ds_write_b64 v148, v[204:205]
	v_max_f32_e32 v216, 0, v104
	v_max_f32_e32 v217, 0, v105
	v_max_f32_e32 v218, 0, v106
	v_max_f32_e32 v219, 0, v107
	v_pk_mul_f32 v[216:217], v[216:217], v[216:217]
	v_pk_mul_f32 v[218:219], v[218:219], v[218:219]
	v_cvt_pk_bf16_f32 v206, v216, v217
	v_cvt_pk_bf16_f32 v207, v218, v219
	ds_write_b64 v149, v[206:207]
	v_max_f32_e32 v212, 0, v100
	v_max_f32_e32 v213, 0, v101
	v_max_f32_e32 v214, 0, v102
	v_max_f32_e32 v215, 0, v103
	v_pk_mul_f32 v[212:213], v[212:213], v[212:213]
	v_pk_mul_f32 v[214:215], v[214:215], v[214:215]
	v_cvt_pk_bf16_f32 v208, v212, v213
	v_cvt_pk_bf16_f32 v209, v214, v215
	ds_write_b64 v150, v[208:209]
	v_max_f32_e32 v216, 0, v96
	v_max_f32_e32 v217, 0, v97
	v_max_f32_e32 v218, 0, v98
	v_max_f32_e32 v219, 0, v99
	v_pk_mul_f32 v[216:217], v[216:217], v[216:217]
	v_pk_mul_f32 v[218:219], v[218:219], v[218:219]
	v_cvt_pk_bf16_f32 v210, v216, v217
	v_cvt_pk_bf16_f32 v211, v218, v219
	ds_write_b64 v151, v[210:211]
	s_waitcnt lgkmcnt(4)
	global_store_dwordx4 v146, v[236:239], s[66:67]
	global_store_dwordx4 v147, v[240:243], s[66:67]
	v_add_u32_e32 v146, s5, v146
	v_add_u32_e32 v147, s5, v147
	ds_read_b128 v[128:131], v156
	ds_read_b128 v[152:155], v156 offset:1024
	v_max_f32_e32 v212, 0, v92
	v_max_f32_e32 v213, 0, v93
	v_max_f32_e32 v214, 0, v94
	v_max_f32_e32 v215, 0, v95
	v_pk_mul_f32 v[212:213], v[212:213], v[212:213]
	v_pk_mul_f32 v[214:215], v[214:215], v[214:215]
	v_cvt_pk_bf16_f32 v204, v212, v213
	v_cvt_pk_bf16_f32 v205, v214, v215
	ds_write_b64 v148, v[204:205]
	v_max_f32_e32 v216, 0, v88
	v_max_f32_e32 v217, 0, v89
	v_max_f32_e32 v218, 0, v90
	v_max_f32_e32 v219, 0, v91
	v_pk_mul_f32 v[216:217], v[216:217], v[216:217]
	v_pk_mul_f32 v[218:219], v[218:219], v[218:219]
	v_cvt_pk_bf16_f32 v206, v216, v217
	v_cvt_pk_bf16_f32 v207, v218, v219
	ds_write_b64 v149, v[206:207]
	v_max_f32_e32 v212, 0, v84
	v_max_f32_e32 v213, 0, v85
	v_max_f32_e32 v214, 0, v86
	v_max_f32_e32 v215, 0, v87
	v_pk_mul_f32 v[212:213], v[212:213], v[212:213]
	v_pk_mul_f32 v[214:215], v[214:215], v[214:215]
	v_cvt_pk_bf16_f32 v208, v212, v213
	v_cvt_pk_bf16_f32 v209, v214, v215
	ds_write_b64 v150, v[208:209]
	v_max_f32_e32 v216, 0, v80
	v_max_f32_e32 v217, 0, v81
	v_max_f32_e32 v218, 0, v82
	v_max_f32_e32 v219, 0, v83
	v_pk_mul_f32 v[216:217], v[216:217], v[216:217]
	v_pk_mul_f32 v[218:219], v[218:219], v[218:219]
	v_cvt_pk_bf16_f32 v210, v216, v217
	v_cvt_pk_bf16_f32 v211, v218, v219
	ds_write_b64 v151, v[210:211]
	s_waitcnt lgkmcnt(4)
; #define EPI_LOOP(MODE) do { _Pragma("unroll") for (int m = 0; m < 8; ++m) _Pragma("unroll") for (int n = 0; n < 4; ++n) \
;         epi_store<MODE>(g, brow + wr * 128 + m * 16 + fr, bcol + wc * 64 + n * 16 + fq * 4, acc[m][n]); } while (0)
; template <int MODE> __device__ __forceinline__ void epi_store(const GemmDesc& g, int row, int col, f32x4 v) {
;     ...
;     case E_SQRELU: {
;       float a = fmaxf(v[0], 0.f), b = fmaxf(v[1], 0.f), c = fmaxf(v[2], 0.f), d = fmaxf(v[3], 0.f);
;       uint2 o; o.x = pack2(a * a, b * b); o.y = pack2(c * c, d * d);
;       *(uint2*)((u16*)g.o0 + (size_t)row * g.ldo + col) = o;
;     } break;
; __device__ __forceinline__ void gemm_run(const GemmDesc& g, char* shm) {
;     ...
;     switch (g.emode) {
;       case E_SQRELU: EPI_LOOP(E_SQRELU); break;
	global_store_dwordx4 v146, v[128:131], s[66:67]
	global_store_dwordx4 v147, v[152:155], s[66:67]
	v_add_u32_e32 v146, s5, v146
	v_add_u32_e32 v147, s5, v147
	ds_read_b128 v[236:239], v156
	ds_read_b128 v[240:243], v156 offset:1024
	v_max_f32_e32 v212, 0, v76
	v_max_f32_e32 v213, 0, v77
	v_max_f32_e32 v214, 0, v78
	v_max_f32_e32 v215, 0, v79
	v_pk_mul_f32 v[212:213], v[212:213], v[212:213]
	v_pk_mul_f32 v[214:215], v[214:215], v[214:215]
	v_cvt_pk_bf16_f32 v204, v212, v213
	v_cvt_pk_bf16_f32 v205, v214, v215
	ds_write_b64 v148, v[204:205]
	v_max_f32_e32 v216, 0, v72
	v_max_f32_e32 v217, 0, v73
	v_max_f32_e32 v218, 0, v74
	v_max_f32_e32 v219, 0, v75
	v_pk_mul_f32 v[216:217], v[216:217], v[216:217]
	v_pk_mul_f32 v[218:219], v[218:219], v[218:219]
	v_cvt_pk_bf16_f32 v206, v216, v217
	v_cvt_pk_bf16_f32 v207, v218, v219
	ds_write_b64 v149, v[206:207]
	v_max_f32_e32 v212, 0, v68
	v_max_f32_e32 v213, 0, v69
	v_max_f32_e32 v214, 0, v70
	v_max_f32_e32 v215, 0, v71
	v_pk_mul_f32 v[212:213], v[212:213], v[212:213]
	v_pk_mul_f32 v[214:215], v[214:215], v[214:215]
	v_cvt_pk_bf16_f32 v208, v212, v213
	v_cvt_pk_bf16_f32 v209, v214, v215
	ds_write_b64 v150, v[208:209]
	v_max_f32_e32 v216, 0, v64
	v_max_f32_e32 v217, 0, v65
	v_max_f32_e32 v218, 0, v66
	v_max_f32_e32 v219, 0, v67
	v_pk_mul_f32 v[216:217], v[216:217], v[216:217]
	v_pk_mul_f32 v[218:219], v[218:219], v[218:219]
	v_cvt_pk_bf16_f32 v210, v216, v217
	v_cvt_pk_bf16_f32 v211, v218, v219
	ds_write_b64 v151, v[210:211]
	s_waitcnt lgkmcnt(4)
	global_store_dwordx4 v146, v[236:239], s[66:67]
	global_store_dwordx4 v147, v[240:243], s[66:67]
	v_add_u32_e32 v146, s5, v146
	v_add_u32_e32 v147, s5, v147
	ds_read_b128 v[128:131], v156
	ds_read_b128 v[152:155], v156 offset:1024
	v_max_f32_e32 v212, 0, v60
	v_max_f32_e32 v213, 0, v61
	v_max_f32_e32 v214, 0, v62
	v_max_f32_e32 v215, 0, v63
	v_pk_mul_f32 v[212:213], v[212:213], v[212:213]
	v_pk_mul_f32 v[214:215], v[214:215], v[214:215]
	v_cvt_pk_bf16_f32 v204, v212, v213
	v_cvt_pk_bf16_f32 v205, v214, v215
	ds_write_b64 v148, v[204:205]
	v_max_f32_e32 v216, 0, v56
	v_max_f32_e32 v217, 0, v57
	v_max_f32_e32 v218, 0, v58
	v_max_f32_e32 v219, 0, v59
	v_pk_mul_f32 v[216:217], v[216:217], v[216:217]
	v_pk_mul_f32 v[218:219], v[218:219], v[218:219]
	v_cvt_pk_bf16_f32 v206, v216, v217
	v_cvt_pk_bf16_f32 v207, v218, v219
	ds_write_b64 v149, v[206:207]
	v_max_f32_e32 v212, 0, v52
	v_max_f32_e32 v213, 0, v53
	v_max_f32_e32 v214, 0, v54
	v_max_f32_e32 v215, 0, v55
	v_pk_mul_f32 v[212:213], v[212:213], v[212:213]
	v_pk_mul_f32 v[214:215], v[214:215], v[214:215]
	v_cvt_pk_bf16_f32 v208, v212, v213
	v_cvt_pk_bf16_f32 v209, v214, v215
	ds_write_b64 v150, v[208:209]
	v_max_f32_e32 v216, 0, v48
	v_max_f32_e32 v217, 0, v49
	v_max_f32_e32 v218, 0, v50
	v_max_f32_e32 v219, 0, v51
	v_pk_mul_f32 v[216:217], v[216:217], v[216:217]
	v_pk_mul_f32 v[218:219], v[218:219], v[218:219]
	v_cvt_pk_bf16_f32 v210, v216, v217
	v_cvt_pk_bf16_f32 v211, v218, v219
	ds_write_b64 v151, v[210:211]
	s_waitcnt lgkmcnt(4)
	global_store_dwordx4 v146, v[128:131], s[66:67]
	global_store_dwordx4 v147, v[152:155], s[66:67]
	v_add_u32_e32 v146, s5, v146
	v_add_u32_e32 v147, s5, v147
	ds_read_b128 v[236:239], v156
	ds_read_b128 v[240:243], v156 offset:1024
	v_max_f32_e32 v212, 0, v44
	v_max_f32_e32 v213, 0, v45
	v_max_f32_e32 v214, 0, v46
	v_max_f32_e32 v215, 0, v47
	v_pk_mul_f32 v[212:213], v[212:213], v[212:213]
	v_pk_mul_f32 v[214:215], v[214:215], v[214:215]
	v_cvt_pk_bf16_f32 v204, v212, v213
	v_cvt_pk_bf16_f32 v205, v214, v215
	ds_write_b64 v148, v[204:205]
	v_max_f32_e32 v216, 0, v40
	v_max_f32_e32 v217, 0, v41
	v_max_f32_e32 v218, 0, v42
	v_max_f32_e32 v219, 0, v43
	v_pk_mul_f32 v[216:217], v[216:217], v[216:217]
	v_pk_mul_f32 v[218:219], v[218:219], v[218:219]
	v_cvt_pk_bf16_f32 v206, v216, v217
	v_cvt_pk_bf16_f32 v207, v218, v219
	ds_write_b64 v149, v[206:207]
	v_max_f32_e32 v212, 0, v36
	v_max_f32_e32 v213, 0, v37
	v_max_f32_e32 v214, 0, v38
	v_max_f32_e32 v215, 0, v39
	v_pk_mul_f32 v[212:213], v[212:213], v[212:213]
	v_pk_mul_f32 v[214:215], v[214:215], v[214:215]
	v_cvt_pk_bf16_f32 v208, v212, v213
	v_cvt_pk_bf16_f32 v209, v214, v215
	ds_write_b64 v150, v[208:209]
	v_max_f32_e32 v216, 0, v32
	v_max_f32_e32 v217, 0, v33
	v_max_f32_e32 v218, 0, v34
	v_max_f32_e32 v219, 0, v35
	v_pk_mul_f32 v[216:217], v[216:217], v[216:217]
	v_pk_mul_f32 v[218:219], v[218:219], v[218:219]
	v_cvt_pk_bf16_f32 v210, v216, v217
	v_cvt_pk_bf16_f32 v211, v218, v219
	ds_write_b64 v151, v[210:211]
	s_waitcnt lgkmcnt(4)
; #define EPI_LOOP(MODE) do { _Pragma("unroll") for (int m = 0; m < 8; ++m) _Pragma("unroll") for (int n = 0; n < 4; ++n) \
;         epi_store<MODE>(g, brow + wr * 128 + m * 16 + fr, bcol + wc * 64 + n * 16 + fq * 4, acc[m][n]); } while (0)
; template <int MODE> __device__ __forceinline__ void epi_store(const GemmDesc& g, int row, int col, f32x4 v) {
;     ...
;     case E_SQRELU: {
;       float a = fmaxf(v[0], 0.f), b = fmaxf(v[1], 0.f), c = fmaxf(v[2], 0.f), d = fmaxf(v[3], 0.f);
;       uint2 o; o.x = pack2(a * a, b * b); o.y = pack2(c * c, d * d);
;       *(uint2*)((u16*)g.o0 + (size_t)row * g.ldo + col) = o;
;     } break;
; __device__ __forceinline__ void gemm_run(const GemmDesc& g, char* shm) {
;     ...
;     switch (g.emode) {
;       case E_SQRELU: EPI_LOOP(E_SQRELU); break;
	global_store_dwordx4 v146, v[236:239], s[66:67]
	global_store_dwordx4 v147, v[240:243], s[66:67]
	v_add_u32_e32 v146, s5, v146
	v_add_u32_e32 v147, s5, v147
	ds_read_b128 v[128:131], v156
	ds_read_b128 v[152:155], v156 offset:1024
	v_max_f32_e32 v212, 0, v28
	v_max_f32_e32 v213, 0, v29
	v_max_f32_e32 v214, 0, v30
	v_max_f32_e32 v215, 0, v31
	v_pk_mul_f32 v[212:213], v[212:213], v[212:213]
	v_pk_mul_f32 v[214:215], v[214:215], v[214:215]
	v_cvt_pk_bf16_f32 v204, v212, v213
	v_cvt_pk_bf16_f32 v205, v214, v215
	ds_write_b64 v148, v[204:205]
	v_max_f32_e32 v216, 0, v24
	v_max_f32_e32 v217, 0, v25
	v_max_f32_e32 v218, 0, v26
	v_max_f32_e32 v219, 0, v27
	v_pk_mul_f32 v[216:217], v[216:217], v[216:217]
	v_pk_mul_f32 v[218:219], v[218:219], v[218:219]
	v_cvt_pk_bf16_f32 v206, v216, v217
	v_cvt_pk_bf16_f32 v207, v218, v219
	ds_write_b64 v149, v[206:207]
	v_max_f32_e32 v212, 0, v20
	v_max_f32_e32 v213, 0, v21
	v_max_f32_e32 v214, 0, v22
	v_max_f32_e32 v215, 0, v23
	v_pk_mul_f32 v[212:213], v[212:213], v[212:213]
	v_pk_mul_f32 v[214:215], v[214:215], v[214:215]
	v_cvt_pk_bf16_f32 v208, v212, v213
	v_cvt_pk_bf16_f32 v209, v214, v215
	ds_write_b64 v150, v[208:209]
	v_max_f32_e32 v216, 0, v16
	v_max_f32_e32 v217, 0, v17
	v_max_f32_e32 v218, 0, v18
	v_max_f32_e32 v219, 0, v19
	v_pk_mul_f32 v[216:217], v[216:217], v[216:217]
	v_pk_mul_f32 v[218:219], v[218:219], v[218:219]
	v_cvt_pk_bf16_f32 v210, v216, v217
	v_cvt_pk_bf16_f32 v211, v218, v219
	ds_write_b64 v151, v[210:211]
	s_waitcnt lgkmcnt(4)
	global_store_dwordx4 v146, v[128:131], s[66:67]
	global_store_dwordx4 v147, v[152:155], s[66:67]
	v_add_u32_e32 v146, s5, v146
	v_add_u32_e32 v147, s5, v147
	ds_read_b128 v[236:239], v156
	ds_read_b128 v[240:243], v156 offset:1024
	v_max_f32_e32 v212, 0, v12
	v_max_f32_e32 v213, 0, v13
	v_max_f32_e32 v214, 0, v14
	v_max_f32_e32 v215, 0, v15
	v_pk_mul_f32 v[212:213], v[212:213], v[212:213]
	v_pk_mul_f32 v[214:215], v[214:215], v[214:215]
	v_cvt_pk_bf16_f32 v204, v212, v213
	v_cvt_pk_bf16_f32 v205, v214, v215
	ds_write_b64 v148, v[204:205]
	v_max_f32_e32 v216, 0, v8
	v_max_f32_e32 v217, 0, v9
	v_max_f32_e32 v218, 0, v10
	v_max_f32_e32 v219, 0, v11
	v_pk_mul_f32 v[216:217], v[216:217], v[216:217]
	v_pk_mul_f32 v[218:219], v[218:219], v[218:219]
	v_cvt_pk_bf16_f32 v206, v216, v217
	v_cvt_pk_bf16_f32 v207, v218, v219
	ds_write_b64 v149, v[206:207]
	v_max_f32_e32 v212, 0, v4
	v_max_f32_e32 v213, 0, v5
	v_max_f32_e32 v214, 0, v6
	v_max_f32_e32 v215, 0, v7
	v_pk_mul_f32 v[212:213], v[212:213], v[212:213]
	v_pk_mul_f32 v[214:215], v[214:215], v[214:215]
	v_cvt_pk_bf16_f32 v208, v212, v213
	v_cvt_pk_bf16_f32 v209, v214, v215
	ds_write_b64 v150, v[208:209]
	v_max_f32_e32 v216, 0, v0
	v_max_f32_e32 v217, 0, v1
	v_max_f32_e32 v218, 0, v2
	v_max_f32_e32 v219, 0, v3
	v_pk_mul_f32 v[216:217], v[216:217], v[216:217]
	v_pk_mul_f32 v[218:219], v[218:219], v[218:219]
	v_cvt_pk_bf16_f32 v210, v216, v217
	v_cvt_pk_bf16_f32 v211, v218, v219
	ds_write_b64 v151, v[210:211]
	s_waitcnt lgkmcnt(4)
	global_store_dwordx4 v146, v[236:239], s[66:67]
	global_store_dwordx4 v147, v[240:243], s[66:67]
	v_add_u32_e32 v146, s5, v146
	v_add_u32_e32 v147, s5, v147
	ds_read_b128 v[128:131], v156
	ds_read_b128 v[152:155], v156 offset:1024
	s_waitcnt lgkmcnt(0)
	global_store_dwordx4 v146, v[128:131], s[66:67]
	global_store_dwordx4 v147, v[152:155], s[66:67]
	s_branch .LBB0_261
